# P0 rmsnorm rewritten by hand: 16-byte bf16 stores, double-buffered 4-row batches with counted vmcnt
# baseline (speedup 1.0000x reference)
.Ltcx_done:
	s_lshl_b32 s3, s2, 5
	s_add_u32 s46, s52, 0x1aa0800
	s_addc_u32 s47, s53, 0
	s_lshl_b32 s54, s33, 5
	s_mov_b64 s[8:9], exec
	v_readfirstlane_b32 s4, v238
	v_and_b32_e32 v2, 63, v238
	v_lshlrev_b32_e32 v22, 5, v2
	v_lshlrev_b32_e32 v23, 4, v2
	v_xor_b32_e32 v16, 32, v2
	v_xor_b32_e32 v17, 16, v2
	v_xor_b32_e32 v18, 8, v2
	v_xor_b32_e32 v19, 4, v2
	v_xor_b32_e32 v20, 2, v2
	v_xor_b32_e32 v21, 1, v2
	v_lshlrev_b32_e32 v16, 2, v16
	v_lshlrev_b32_e32 v17, 2, v17
	v_lshlrev_b32_e32 v18, 2, v18
	v_lshlrev_b32_e32 v19, 2, v19
	v_lshlrev_b32_e32 v20, 2, v20
	v_lshlrev_b32_e32 v21, 2, v21
	v_mov_b32_e32 v220, 0x358637bd
	s_lshr_b32 s4, s4, 6
	s_lshl_b32 s16, s4, 2
	s_add_i32 s16, s16, s3
	s_mov_b32 s5, 0x8000
	s_cmp_lt_u32 s16, s5
	s_cbranch_scc0 .Lrms_done
	global_load_dwordx4 v[100:103], v22, s[14:15]
	global_load_dwordx4 v[104:107], v22, s[14:15] offset:16
	global_load_dwordx4 v[108:111], v22, s[14:15] offset:2048
	global_load_dwordx4 v[112:115], v22, s[14:15] offset:2064
	s_mov_b32 s7, 0x800000
	s_lshl_b32 s6, s16, 12
	s_add_u32 s18, s12, s6
	s_addc_u32 s19, s13, 0
	s_add_u32 s20, s18, 0x1000
	s_addc_u32 s21, s19, 0
	s_add_u32 s22, s20, 0x1000
	s_addc_u32 s23, s21, 0
	s_add_u32 s24, s22, 0x1000
	s_addc_u32 s25, s23, 0
	global_load_dwordx4 v[116:119], v22, s[18:19]
	global_load_dwordx4 v[120:123], v22, s[18:19] offset:16
	global_load_dwordx4 v[124:127], v22, s[18:19] offset:2048
	global_load_dwordx4 v[128:131], v22, s[18:19] offset:2064
	global_load_dwordx4 v[132:135], v22, s[20:21]
	global_load_dwordx4 v[136:139], v22, s[20:21] offset:16
	global_load_dwordx4 v[140:143], v22, s[20:21] offset:2048
	global_load_dwordx4 v[144:147], v22, s[20:21] offset:2064
	global_load_dwordx4 v[148:151], v22, s[22:23]
	global_load_dwordx4 v[152:155], v22, s[22:23] offset:16
	global_load_dwordx4 v[156:159], v22, s[22:23] offset:2048
	global_load_dwordx4 v[160:163], v22, s[22:23] offset:2064
	global_load_dwordx4 v[164:167], v22, s[24:25]
	global_load_dwordx4 v[168:171], v22, s[24:25] offset:16
	global_load_dwordx4 v[172:175], v22, s[24:25] offset:2048
	global_load_dwordx4 v[176:179], v22, s[24:25] offset:2064
	s_add_i32 s17, s16, s54
	s_cmp_lt_u32 s17, s5
	s_cbranch_scc0 .Lrms_f_last
	s_lshl_b32 s6, s17, 12
	s_add_u32 s18, s12, s6
	s_addc_u32 s19, s13, 0
	s_add_u32 s20, s18, 0x1000
	s_addc_u32 s21, s19, 0
	s_add_u32 s22, s20, 0x1000
	s_addc_u32 s23, s21, 0
	s_add_u32 s24, s22, 0x1000
	s_addc_u32 s25, s23, 0
	global_load_dwordx4 v[24:27], v22, s[18:19]
	global_load_dwordx4 v[28:31], v22, s[18:19] offset:16
	global_load_dwordx4 v[32:35], v22, s[18:19] offset:2048
	global_load_dwordx4 v[36:39], v22, s[18:19] offset:2064
	global_load_dwordx4 v[40:43], v22, s[20:21]
	global_load_dwordx4 v[44:47], v22, s[20:21] offset:16
	global_load_dwordx4 v[48:51], v22, s[20:21] offset:2048
	global_load_dwordx4 v[52:55], v22, s[20:21] offset:2064
	global_load_dwordx4 v[56:59], v22, s[22:23]
	global_load_dwordx4 v[60:63], v22, s[22:23] offset:16
	global_load_dwordx4 v[64:67], v22, s[22:23] offset:2048
	global_load_dwordx4 v[68:71], v22, s[22:23] offset:2064
	global_load_dwordx4 v[72:75], v22, s[24:25]
	global_load_dwordx4 v[76:79], v22, s[24:25] offset:16
	global_load_dwordx4 v[80:83], v22, s[24:25] offset:2048
	global_load_dwordx4 v[84:87], v22, s[24:25] offset:2064
	s_waitcnt vmcnt(16)
	v_mul_f32_e32 v8, v116, v116
	v_mul_f32_e32 v9, v132, v132
	v_mul_f32_e32 v10, v148, v148
	v_mul_f32_e32 v11, v164, v164
	v_fmac_f32_e32 v8, v117, v117
	v_fmac_f32_e32 v9, v133, v133
	v_fmac_f32_e32 v10, v149, v149
	v_fmac_f32_e32 v11, v165, v165
	v_fmac_f32_e32 v8, v118, v118
	v_fmac_f32_e32 v9, v134, v134
	v_fmac_f32_e32 v10, v150, v150
	v_fmac_f32_e32 v11, v166, v166
	v_fmac_f32_e32 v8, v119, v119
	v_fmac_f32_e32 v9, v135, v135
	v_fmac_f32_e32 v10, v151, v151
	v_fmac_f32_e32 v11, v167, v167
	v_fmac_f32_e32 v8, v120, v120
	v_fmac_f32_e32 v9, v136, v136
	v_fmac_f32_e32 v10, v152, v152
	v_fmac_f32_e32 v11, v168, v168
	v_fmac_f32_e32 v8, v121, v121
	v_fmac_f32_e32 v9, v137, v137
	v_fmac_f32_e32 v10, v153, v153
	v_fmac_f32_e32 v11, v169, v169
	v_fmac_f32_e32 v8, v122, v122
	v_fmac_f32_e32 v9, v138, v138
	v_fmac_f32_e32 v10, v154, v154
	v_fmac_f32_e32 v11, v170, v170
	v_fmac_f32_e32 v8, v123, v123
	v_fmac_f32_e32 v9, v139, v139
	v_fmac_f32_e32 v10, v155, v155
	v_fmac_f32_e32 v11, v171, v171
	v_fmac_f32_e32 v8, v124, v124
	v_fmac_f32_e32 v9, v140, v140
	v_fmac_f32_e32 v10, v156, v156
	v_fmac_f32_e32 v11, v172, v172
	v_fmac_f32_e32 v8, v125, v125
	v_fmac_f32_e32 v9, v141, v141
	v_fmac_f32_e32 v10, v157, v157
	v_fmac_f32_e32 v11, v173, v173
	v_fmac_f32_e32 v8, v126, v126
	v_fmac_f32_e32 v9, v142, v142
	v_fmac_f32_e32 v10, v158, v158
	v_fmac_f32_e32 v11, v174, v174
	v_fmac_f32_e32 v8, v127, v127
	v_fmac_f32_e32 v9, v143, v143
	v_fmac_f32_e32 v10, v159, v159
	v_fmac_f32_e32 v11, v175, v175
	v_fmac_f32_e32 v8, v128, v128
	v_fmac_f32_e32 v9, v144, v144
	v_fmac_f32_e32 v10, v160, v160
	v_fmac_f32_e32 v11, v176, v176
	v_fmac_f32_e32 v8, v129, v129
	v_fmac_f32_e32 v9, v145, v145
	v_fmac_f32_e32 v10, v161, v161
	v_fmac_f32_e32 v11, v177, v177
	v_fmac_f32_e32 v8, v130, v130
	v_fmac_f32_e32 v9, v146, v146
	v_fmac_f32_e32 v10, v162, v162
	v_fmac_f32_e32 v11, v178, v178
	v_fmac_f32_e32 v8, v131, v131
	v_fmac_f32_e32 v9, v147, v147
	v_fmac_f32_e32 v10, v163, v163
	v_fmac_f32_e32 v11, v179, v179
	ds_bpermute_b32 v12, v16, v8
	ds_bpermute_b32 v13, v16, v9
	ds_bpermute_b32 v14, v16, v10
	ds_bpermute_b32 v15, v16, v11
	s_waitcnt lgkmcnt(0)
	v_add_f32_e32 v8, v8, v12
	v_add_f32_e32 v9, v9, v13
	v_add_f32_e32 v10, v10, v14
	v_add_f32_e32 v11, v11, v15
	ds_bpermute_b32 v12, v17, v8
	ds_bpermute_b32 v13, v17, v9
	ds_bpermute_b32 v14, v17, v10
	ds_bpermute_b32 v15, v17, v11
	s_waitcnt lgkmcnt(0)
	v_add_f32_e32 v8, v8, v12
	v_add_f32_e32 v9, v9, v13
	v_add_f32_e32 v10, v10, v14
	v_add_f32_e32 v11, v11, v15
	ds_bpermute_b32 v12, v18, v8
	ds_bpermute_b32 v13, v18, v9
	ds_bpermute_b32 v14, v18, v10
	ds_bpermute_b32 v15, v18, v11
	s_waitcnt lgkmcnt(0)
	v_add_f32_e32 v8, v8, v12
	v_add_f32_e32 v9, v9, v13
	v_add_f32_e32 v10, v10, v14
	v_add_f32_e32 v11, v11, v15
	ds_bpermute_b32 v12, v19, v8
	ds_bpermute_b32 v13, v19, v9
	ds_bpermute_b32 v14, v19, v10
	ds_bpermute_b32 v15, v19, v11
	s_waitcnt lgkmcnt(0)
	v_add_f32_e32 v8, v8, v12
	v_add_f32_e32 v9, v9, v13
	v_add_f32_e32 v10, v10, v14
	v_add_f32_e32 v11, v11, v15
	ds_bpermute_b32 v12, v20, v8
	ds_bpermute_b32 v13, v20, v9
	ds_bpermute_b32 v14, v20, v10
	ds_bpermute_b32 v15, v20, v11
	s_waitcnt lgkmcnt(0)
	v_add_f32_e32 v8, v8, v12
	v_add_f32_e32 v9, v9, v13
	v_add_f32_e32 v10, v10, v14
	v_add_f32_e32 v11, v11, v15
	ds_bpermute_b32 v12, v21, v8
	ds_bpermute_b32 v13, v21, v9
	ds_bpermute_b32 v14, v21, v10
	ds_bpermute_b32 v15, v21, v11
	s_waitcnt lgkmcnt(0)
	v_add_f32_e32 v8, v8, v12
	v_add_f32_e32 v9, v9, v13
	v_add_f32_e32 v10, v10, v14
	v_add_f32_e32 v11, v11, v15
	v_fmamk_f32 v8, v8, 0x3a800000, v220
	v_fmamk_f32 v9, v9, 0x3a800000, v220
	v_fmamk_f32 v10, v10, 0x3a800000, v220
	v_fmamk_f32 v11, v11, 0x3a800000, v220
	v_mul_f32_e32 v12, 0x4b800000, v8
	v_mul_f32_e32 v13, 0x4b800000, v9
	v_mul_f32_e32 v14, 0x4b800000, v10
	v_mul_f32_e32 v15, 0x4b800000, v11
	v_cmp_gt_f32_e32 vcc, s7, v8
	s_nop 1
	v_cndmask_b32_e32 v8, v8, v12, vcc
	v_rsq_f32_e32 v212, v8
	s_nop 0
	v_mul_f32_e32 v216, 0x45800000, v212
	v_cndmask_b32_e32 v212, v212, v216, vcc
	v_cmp_gt_f32_e32 vcc, s7, v9
	s_nop 1
	v_cndmask_b32_e32 v9, v9, v13, vcc
	v_rsq_f32_e32 v213, v9
	s_nop 0
	v_mul_f32_e32 v216, 0x45800000, v213
	v_cndmask_b32_e32 v213, v213, v216, vcc
	v_cmp_gt_f32_e32 vcc, s7, v10
	s_nop 1
	v_cndmask_b32_e32 v10, v10, v14, vcc
	v_rsq_f32_e32 v214, v10
	s_nop 0
	v_mul_f32_e32 v216, 0x45800000, v214
	v_cndmask_b32_e32 v214, v214, v216, vcc
	v_cmp_gt_f32_e32 vcc, s7, v11
	s_nop 1
	v_cndmask_b32_e32 v11, v11, v15, vcc
	v_rsq_f32_e32 v215, v11
	s_nop 0
	v_mul_f32_e32 v216, 0x45800000, v215
	v_cndmask_b32_e32 v215, v215, v216, vcc
	s_lshl_b32 s6, s16, 11
	s_add_u32 s26, s46, s6
	s_addc_u32 s27, s47, 0
	s_add_u32 s30, s26, 0x1000
	s_addc_u32 s31, s27, 0
	v_mul_f32_e32 v116, v116, v212
	v_mul_f32_e32 v117, v117, v212
	v_mul_f32_e32 v118, v118, v212
	v_mul_f32_e32 v119, v119, v212
	v_mul_f32_e32 v120, v120, v212
	v_mul_f32_e32 v121, v121, v212
	v_mul_f32_e32 v122, v122, v212
	v_mul_f32_e32 v123, v123, v212
	v_mul_f32_e32 v124, v124, v212
	v_mul_f32_e32 v125, v125, v212
	v_mul_f32_e32 v126, v126, v212
	v_mul_f32_e32 v127, v127, v212
	v_mul_f32_e32 v128, v128, v212
	v_mul_f32_e32 v129, v129, v212
	v_mul_f32_e32 v130, v130, v212
	v_mul_f32_e32 v131, v131, v212
	v_mul_f32_e32 v116, v100, v116
	v_mul_f32_e32 v117, v101, v117
	v_mul_f32_e32 v118, v102, v118
	v_mul_f32_e32 v119, v103, v119
	v_mul_f32_e32 v120, v104, v120
	v_mul_f32_e32 v121, v105, v121
	v_mul_f32_e32 v122, v106, v122
	v_mul_f32_e32 v123, v107, v123
	v_mul_f32_e32 v124, v108, v124
	v_mul_f32_e32 v125, v109, v125
	v_mul_f32_e32 v126, v110, v126
	v_mul_f32_e32 v127, v111, v127
	v_mul_f32_e32 v128, v112, v128
	v_mul_f32_e32 v129, v113, v129
	v_mul_f32_e32 v130, v114, v130
	v_mul_f32_e32 v131, v115, v131
	v_cvt_pk_bf16_f32 v180, v116, v117
	v_cvt_pk_bf16_f32 v181, v118, v119
	v_cvt_pk_bf16_f32 v182, v120, v121
	v_cvt_pk_bf16_f32 v183, v122, v123
	v_cvt_pk_bf16_f32 v184, v124, v125
	v_cvt_pk_bf16_f32 v185, v126, v127
	v_cvt_pk_bf16_f32 v186, v128, v129
	v_cvt_pk_bf16_f32 v187, v130, v131
	global_store_dwordx4 v23, v[180:183], s[26:27]
	global_store_dwordx4 v23, v[184:187], s[26:27] offset:1024
	v_mul_f32_e32 v132, v132, v213
	v_mul_f32_e32 v133, v133, v213
	v_mul_f32_e32 v134, v134, v213
	v_mul_f32_e32 v135, v135, v213
	v_mul_f32_e32 v136, v136, v213
	v_mul_f32_e32 v137, v137, v213
	v_mul_f32_e32 v138, v138, v213
	v_mul_f32_e32 v139, v139, v213
	v_mul_f32_e32 v140, v140, v213
	v_mul_f32_e32 v141, v141, v213
	v_mul_f32_e32 v142, v142, v213
	v_mul_f32_e32 v143, v143, v213
	v_mul_f32_e32 v144, v144, v213
	v_mul_f32_e32 v145, v145, v213
	v_mul_f32_e32 v146, v146, v213
	v_mul_f32_e32 v147, v147, v213
	v_mul_f32_e32 v132, v100, v132
	v_mul_f32_e32 v133, v101, v133
	v_mul_f32_e32 v134, v102, v134
	v_mul_f32_e32 v135, v103, v135
	v_mul_f32_e32 v136, v104, v136
	v_mul_f32_e32 v137, v105, v137
	v_mul_f32_e32 v138, v106, v138
	v_mul_f32_e32 v139, v107, v139
	v_mul_f32_e32 v140, v108, v140
	v_mul_f32_e32 v141, v109, v141
	v_mul_f32_e32 v142, v110, v142
	v_mul_f32_e32 v143, v111, v143
	v_mul_f32_e32 v144, v112, v144
	v_mul_f32_e32 v145, v113, v145
	v_mul_f32_e32 v146, v114, v146
	v_mul_f32_e32 v147, v115, v147
	v_cvt_pk_bf16_f32 v188, v132, v133
	v_cvt_pk_bf16_f32 v189, v134, v135
	v_cvt_pk_bf16_f32 v190, v136, v137
	v_cvt_pk_bf16_f32 v191, v138, v139
	v_cvt_pk_bf16_f32 v192, v140, v141
	v_cvt_pk_bf16_f32 v193, v142, v143
	v_cvt_pk_bf16_f32 v194, v144, v145
	v_cvt_pk_bf16_f32 v195, v146, v147
	global_store_dwordx4 v23, v[188:191], s[26:27] offset:2048
	global_store_dwordx4 v23, v[192:195], s[26:27] offset:3072
	v_mul_f32_e32 v148, v148, v214
	v_mul_f32_e32 v149, v149, v214
	v_mul_f32_e32 v150, v150, v214
	v_mul_f32_e32 v151, v151, v214
	v_mul_f32_e32 v152, v152, v214
	v_mul_f32_e32 v153, v153, v214
	v_mul_f32_e32 v154, v154, v214
	v_mul_f32_e32 v155, v155, v214
	v_mul_f32_e32 v156, v156, v214
	v_mul_f32_e32 v157, v157, v214
	v_mul_f32_e32 v158, v158, v214
	v_mul_f32_e32 v159, v159, v214
	v_mul_f32_e32 v160, v160, v214
	v_mul_f32_e32 v161, v161, v214
	v_mul_f32_e32 v162, v162, v214
	v_mul_f32_e32 v163, v163, v214
	v_mul_f32_e32 v148, v100, v148
	v_mul_f32_e32 v149, v101, v149
	v_mul_f32_e32 v150, v102, v150
	v_mul_f32_e32 v151, v103, v151
	v_mul_f32_e32 v152, v104, v152
	v_mul_f32_e32 v153, v105, v153
	v_mul_f32_e32 v154, v106, v154
	v_mul_f32_e32 v155, v107, v155
	v_mul_f32_e32 v156, v108, v156
	v_mul_f32_e32 v157, v109, v157
	v_mul_f32_e32 v158, v110, v158
	v_mul_f32_e32 v159, v111, v159
	v_mul_f32_e32 v160, v112, v160
	v_mul_f32_e32 v161, v113, v161
	v_mul_f32_e32 v162, v114, v162
	v_mul_f32_e32 v163, v115, v163
	v_cvt_pk_bf16_f32 v196, v148, v149
	v_cvt_pk_bf16_f32 v197, v150, v151
	v_cvt_pk_bf16_f32 v198, v152, v153
	v_cvt_pk_bf16_f32 v199, v154, v155
	v_cvt_pk_bf16_f32 v200, v156, v157
	v_cvt_pk_bf16_f32 v201, v158, v159
	v_cvt_pk_bf16_f32 v202, v160, v161
	v_cvt_pk_bf16_f32 v203, v162, v163
	global_store_dwordx4 v23, v[196:199], s[30:31]
	global_store_dwordx4 v23, v[200:203], s[30:31] offset:1024
	v_mul_f32_e32 v164, v164, v215
	v_mul_f32_e32 v165, v165, v215
	v_mul_f32_e32 v166, v166, v215
	v_mul_f32_e32 v167, v167, v215
	v_mul_f32_e32 v168, v168, v215
	v_mul_f32_e32 v169, v169, v215
	v_mul_f32_e32 v170, v170, v215
	v_mul_f32_e32 v171, v171, v215
	v_mul_f32_e32 v172, v172, v215
	v_mul_f32_e32 v173, v173, v215
	v_mul_f32_e32 v174, v174, v215
	v_mul_f32_e32 v175, v175, v215
	v_mul_f32_e32 v176, v176, v215
	v_mul_f32_e32 v177, v177, v215
	v_mul_f32_e32 v178, v178, v215
	v_mul_f32_e32 v179, v179, v215
	v_mul_f32_e32 v164, v100, v164
	v_mul_f32_e32 v165, v101, v165
	v_mul_f32_e32 v166, v102, v166
	v_mul_f32_e32 v167, v103, v167
	v_mul_f32_e32 v168, v104, v168
	v_mul_f32_e32 v169, v105, v169
	v_mul_f32_e32 v170, v106, v170
	v_mul_f32_e32 v171, v107, v171
	v_mul_f32_e32 v172, v108, v172
	v_mul_f32_e32 v173, v109, v173
	v_mul_f32_e32 v174, v110, v174
	v_mul_f32_e32 v175, v111, v175
	v_mul_f32_e32 v176, v112, v176
	v_mul_f32_e32 v177, v113, v177
	v_mul_f32_e32 v178, v114, v178
	v_mul_f32_e32 v179, v115, v179
	v_cvt_pk_bf16_f32 v204, v164, v165
	v_cvt_pk_bf16_f32 v205, v166, v167
	v_cvt_pk_bf16_f32 v206, v168, v169
	v_cvt_pk_bf16_f32 v207, v170, v171
	v_cvt_pk_bf16_f32 v208, v172, v173
	v_cvt_pk_bf16_f32 v209, v174, v175
	v_cvt_pk_bf16_f32 v210, v176, v177
	v_cvt_pk_bf16_f32 v211, v178, v179
	global_store_dwordx4 v23, v[204:207], s[30:31] offset:2048
	global_store_dwordx4 v23, v[208:211], s[30:31] offset:3072
	s_mov_b32 s16, s17
	s_branch .Lrms_loop1
.Lrms_f_last:
	s_waitcnt vmcnt(0)
	v_mul_f32_e32 v8, v116, v116
	v_mul_f32_e32 v9, v132, v132
	v_mul_f32_e32 v10, v148, v148
	v_mul_f32_e32 v11, v164, v164
	v_fmac_f32_e32 v8, v117, v117
	v_fmac_f32_e32 v9, v133, v133
	v_fmac_f32_e32 v10, v149, v149
	v_fmac_f32_e32 v11, v165, v165
	v_fmac_f32_e32 v8, v118, v118
	v_fmac_f32_e32 v9, v134, v134
	v_fmac_f32_e32 v10, v150, v150
	v_fmac_f32_e32 v11, v166, v166
	v_fmac_f32_e32 v8, v119, v119
	v_fmac_f32_e32 v9, v135, v135
	v_fmac_f32_e32 v10, v151, v151
	v_fmac_f32_e32 v11, v167, v167
	v_fmac_f32_e32 v8, v120, v120
	v_fmac_f32_e32 v9, v136, v136
	v_fmac_f32_e32 v10, v152, v152
	v_fmac_f32_e32 v11, v168, v168
	v_fmac_f32_e32 v8, v121, v121
	v_fmac_f32_e32 v9, v137, v137
	v_fmac_f32_e32 v10, v153, v153
	v_fmac_f32_e32 v11, v169, v169
	v_fmac_f32_e32 v8, v122, v122
	v_fmac_f32_e32 v9, v138, v138
	v_fmac_f32_e32 v10, v154, v154
	v_fmac_f32_e32 v11, v170, v170
	v_fmac_f32_e32 v8, v123, v123
	v_fmac_f32_e32 v9, v139, v139
	v_fmac_f32_e32 v10, v155, v155
	v_fmac_f32_e32 v11, v171, v171
	v_fmac_f32_e32 v8, v124, v124
	v_fmac_f32_e32 v9, v140, v140
	v_fmac_f32_e32 v10, v156, v156
	v_fmac_f32_e32 v11, v172, v172
	v_fmac_f32_e32 v8, v125, v125
	v_fmac_f32_e32 v9, v141, v141
	v_fmac_f32_e32 v10, v157, v157
	v_fmac_f32_e32 v11, v173, v173
	v_fmac_f32_e32 v8, v126, v126
	v_fmac_f32_e32 v9, v142, v142
	v_fmac_f32_e32 v10, v158, v158
	v_fmac_f32_e32 v11, v174, v174
	v_fmac_f32_e32 v8, v127, v127
	v_fmac_f32_e32 v9, v143, v143
	v_fmac_f32_e32 v10, v159, v159
	v_fmac_f32_e32 v11, v175, v175
	v_fmac_f32_e32 v8, v128, v128
	v_fmac_f32_e32 v9, v144, v144
	v_fmac_f32_e32 v10, v160, v160
	v_fmac_f32_e32 v11, v176, v176
	v_fmac_f32_e32 v8, v129, v129
	v_fmac_f32_e32 v9, v145, v145
	v_fmac_f32_e32 v10, v161, v161
	v_fmac_f32_e32 v11, v177, v177
	v_fmac_f32_e32 v8, v130, v130
	v_fmac_f32_e32 v9, v146, v146
	v_fmac_f32_e32 v10, v162, v162
	v_fmac_f32_e32 v11, v178, v178
	v_fmac_f32_e32 v8, v131, v131
	v_fmac_f32_e32 v9, v147, v147
	v_fmac_f32_e32 v10, v163, v163
	v_fmac_f32_e32 v11, v179, v179
	ds_bpermute_b32 v12, v16, v8
	ds_bpermute_b32 v13, v16, v9
	ds_bpermute_b32 v14, v16, v10
	ds_bpermute_b32 v15, v16, v11
	s_waitcnt lgkmcnt(0)
	v_add_f32_e32 v8, v8, v12
	v_add_f32_e32 v9, v9, v13
	v_add_f32_e32 v10, v10, v14
	v_add_f32_e32 v11, v11, v15
	ds_bpermute_b32 v12, v17, v8
	ds_bpermute_b32 v13, v17, v9
	ds_bpermute_b32 v14, v17, v10
	ds_bpermute_b32 v15, v17, v11
	s_waitcnt lgkmcnt(0)
	v_add_f32_e32 v8, v8, v12
	v_add_f32_e32 v9, v9, v13
	v_add_f32_e32 v10, v10, v14
	v_add_f32_e32 v11, v11, v15
	ds_bpermute_b32 v12, v18, v8
	ds_bpermute_b32 v13, v18, v9
	ds_bpermute_b32 v14, v18, v10
	ds_bpermute_b32 v15, v18, v11
	s_waitcnt lgkmcnt(0)
	v_add_f32_e32 v8, v8, v12
	v_add_f32_e32 v9, v9, v13
	v_add_f32_e32 v10, v10, v14
	v_add_f32_e32 v11, v11, v15
	ds_bpermute_b32 v12, v19, v8
	ds_bpermute_b32 v13, v19, v9
	ds_bpermute_b32 v14, v19, v10
	ds_bpermute_b32 v15, v19, v11
	s_waitcnt lgkmcnt(0)
	v_add_f32_e32 v8, v8, v12
	v_add_f32_e32 v9, v9, v13
	v_add_f32_e32 v10, v10, v14
	v_add_f32_e32 v11, v11, v15
	ds_bpermute_b32 v12, v20, v8
	ds_bpermute_b32 v13, v20, v9
	ds_bpermute_b32 v14, v20, v10
	ds_bpermute_b32 v15, v20, v11
	s_waitcnt lgkmcnt(0)
	v_add_f32_e32 v8, v8, v12
	v_add_f32_e32 v9, v9, v13
	v_add_f32_e32 v10, v10, v14
	v_add_f32_e32 v11, v11, v15
	ds_bpermute_b32 v12, v21, v8
	ds_bpermute_b32 v13, v21, v9
	ds_bpermute_b32 v14, v21, v10
	ds_bpermute_b32 v15, v21, v11
	s_waitcnt lgkmcnt(0)
	v_add_f32_e32 v8, v8, v12
	v_add_f32_e32 v9, v9, v13
	v_add_f32_e32 v10, v10, v14
	v_add_f32_e32 v11, v11, v15
	v_fmamk_f32 v8, v8, 0x3a800000, v220
	v_fmamk_f32 v9, v9, 0x3a800000, v220
	v_fmamk_f32 v10, v10, 0x3a800000, v220
	v_fmamk_f32 v11, v11, 0x3a800000, v220
	v_mul_f32_e32 v12, 0x4b800000, v8
	v_mul_f32_e32 v13, 0x4b800000, v9
	v_mul_f32_e32 v14, 0x4b800000, v10
	v_mul_f32_e32 v15, 0x4b800000, v11
	v_cmp_gt_f32_e32 vcc, s7, v8
	s_nop 1
	v_cndmask_b32_e32 v8, v8, v12, vcc
	v_rsq_f32_e32 v212, v8
	s_nop 0
	v_mul_f32_e32 v216, 0x45800000, v212
	v_cndmask_b32_e32 v212, v212, v216, vcc
	v_cmp_gt_f32_e32 vcc, s7, v9
	s_nop 1
	v_cndmask_b32_e32 v9, v9, v13, vcc
	v_rsq_f32_e32 v213, v9
	s_nop 0
	v_mul_f32_e32 v216, 0x45800000, v213
	v_cndmask_b32_e32 v213, v213, v216, vcc
	v_cmp_gt_f32_e32 vcc, s7, v10
	s_nop 1
	v_cndmask_b32_e32 v10, v10, v14, vcc
	v_rsq_f32_e32 v214, v10
	s_nop 0
	v_mul_f32_e32 v216, 0x45800000, v214
	v_cndmask_b32_e32 v214, v214, v216, vcc
	v_cmp_gt_f32_e32 vcc, s7, v11
	s_nop 1
	v_cndmask_b32_e32 v11, v11, v15, vcc
	v_rsq_f32_e32 v215, v11
	s_nop 0
	v_mul_f32_e32 v216, 0x45800000, v215
	v_cndmask_b32_e32 v215, v215, v216, vcc
	s_lshl_b32 s6, s16, 11
	s_add_u32 s26, s46, s6
	s_addc_u32 s27, s47, 0
	s_add_u32 s30, s26, 0x1000
	s_addc_u32 s31, s27, 0
	v_mul_f32_e32 v116, v116, v212
	v_mul_f32_e32 v117, v117, v212
	v_mul_f32_e32 v118, v118, v212
	v_mul_f32_e32 v119, v119, v212
	v_mul_f32_e32 v120, v120, v212
	v_mul_f32_e32 v121, v121, v212
	v_mul_f32_e32 v122, v122, v212
	v_mul_f32_e32 v123, v123, v212
	v_mul_f32_e32 v124, v124, v212
	v_mul_f32_e32 v125, v125, v212
	v_mul_f32_e32 v126, v126, v212
	v_mul_f32_e32 v127, v127, v212
	v_mul_f32_e32 v128, v128, v212
	v_mul_f32_e32 v129, v129, v212
	v_mul_f32_e32 v130, v130, v212
	v_mul_f32_e32 v131, v131, v212
	v_mul_f32_e32 v116, v100, v116
	v_mul_f32_e32 v117, v101, v117
	v_mul_f32_e32 v118, v102, v118
	v_mul_f32_e32 v119, v103, v119
	v_mul_f32_e32 v120, v104, v120
	v_mul_f32_e32 v121, v105, v121
	v_mul_f32_e32 v122, v106, v122
	v_mul_f32_e32 v123, v107, v123
	v_mul_f32_e32 v124, v108, v124
	v_mul_f32_e32 v125, v109, v125
	v_mul_f32_e32 v126, v110, v126
	v_mul_f32_e32 v127, v111, v127
	v_mul_f32_e32 v128, v112, v128
	v_mul_f32_e32 v129, v113, v129
	v_mul_f32_e32 v130, v114, v130
	v_mul_f32_e32 v131, v115, v131
	v_cvt_pk_bf16_f32 v180, v116, v117
	v_cvt_pk_bf16_f32 v181, v118, v119
	v_cvt_pk_bf16_f32 v182, v120, v121
	v_cvt_pk_bf16_f32 v183, v122, v123
	v_cvt_pk_bf16_f32 v184, v124, v125
	v_cvt_pk_bf16_f32 v185, v126, v127
	v_cvt_pk_bf16_f32 v186, v128, v129
	v_cvt_pk_bf16_f32 v187, v130, v131
	global_store_dwordx4 v23, v[180:183], s[26:27]
	global_store_dwordx4 v23, v[184:187], s[26:27] offset:1024
	v_mul_f32_e32 v132, v132, v213
	v_mul_f32_e32 v133, v133, v213
	v_mul_f32_e32 v134, v134, v213
	v_mul_f32_e32 v135, v135, v213
	v_mul_f32_e32 v136, v136, v213
	v_mul_f32_e32 v137, v137, v213
	v_mul_f32_e32 v138, v138, v213
	v_mul_f32_e32 v139, v139, v213
	v_mul_f32_e32 v140, v140, v213
	v_mul_f32_e32 v141, v141, v213
	v_mul_f32_e32 v142, v142, v213
	v_mul_f32_e32 v143, v143, v213
	v_mul_f32_e32 v144, v144, v213
	v_mul_f32_e32 v145, v145, v213
	v_mul_f32_e32 v146, v146, v213
	v_mul_f32_e32 v147, v147, v213
	v_mul_f32_e32 v132, v100, v132
	v_mul_f32_e32 v133, v101, v133
	v_mul_f32_e32 v134, v102, v134
	v_mul_f32_e32 v135, v103, v135
	v_mul_f32_e32 v136, v104, v136
	v_mul_f32_e32 v137, v105, v137
	v_mul_f32_e32 v138, v106, v138
	v_mul_f32_e32 v139, v107, v139
	v_mul_f32_e32 v140, v108, v140
	v_mul_f32_e32 v141, v109, v141
	v_mul_f32_e32 v142, v110, v142
	v_mul_f32_e32 v143, v111, v143
	v_mul_f32_e32 v144, v112, v144
	v_mul_f32_e32 v145, v113, v145
	v_mul_f32_e32 v146, v114, v146
	v_mul_f32_e32 v147, v115, v147
	v_cvt_pk_bf16_f32 v188, v132, v133
	v_cvt_pk_bf16_f32 v189, v134, v135
	v_cvt_pk_bf16_f32 v190, v136, v137
	v_cvt_pk_bf16_f32 v191, v138, v139
	v_cvt_pk_bf16_f32 v192, v140, v141
	v_cvt_pk_bf16_f32 v193, v142, v143
	v_cvt_pk_bf16_f32 v194, v144, v145
	v_cvt_pk_bf16_f32 v195, v146, v147
	global_store_dwordx4 v23, v[188:191], s[26:27] offset:2048
	global_store_dwordx4 v23, v[192:195], s[26:27] offset:3072
	v_mul_f32_e32 v148, v148, v214
	v_mul_f32_e32 v149, v149, v214
	v_mul_f32_e32 v150, v150, v214
	v_mul_f32_e32 v151, v151, v214
	v_mul_f32_e32 v152, v152, v214
	v_mul_f32_e32 v153, v153, v214
	v_mul_f32_e32 v154, v154, v214
	v_mul_f32_e32 v155, v155, v214
	v_mul_f32_e32 v156, v156, v214
	v_mul_f32_e32 v157, v157, v214
	v_mul_f32_e32 v158, v158, v214
	v_mul_f32_e32 v159, v159, v214
	v_mul_f32_e32 v160, v160, v214
	v_mul_f32_e32 v161, v161, v214
	v_mul_f32_e32 v162, v162, v214
	v_mul_f32_e32 v163, v163, v214
	v_mul_f32_e32 v148, v100, v148
	v_mul_f32_e32 v149, v101, v149
	v_mul_f32_e32 v150, v102, v150
	v_mul_f32_e32 v151, v103, v151
	v_mul_f32_e32 v152, v104, v152
	v_mul_f32_e32 v153, v105, v153
	v_mul_f32_e32 v154, v106, v154
	v_mul_f32_e32 v155, v107, v155
	v_mul_f32_e32 v156, v108, v156
	v_mul_f32_e32 v157, v109, v157
	v_mul_f32_e32 v158, v110, v158
	v_mul_f32_e32 v159, v111, v159
	v_mul_f32_e32 v160, v112, v160
	v_mul_f32_e32 v161, v113, v161
	v_mul_f32_e32 v162, v114, v162
	v_mul_f32_e32 v163, v115, v163
	v_cvt_pk_bf16_f32 v196, v148, v149
	v_cvt_pk_bf16_f32 v197, v150, v151
	v_cvt_pk_bf16_f32 v198, v152, v153
	v_cvt_pk_bf16_f32 v199, v154, v155
	v_cvt_pk_bf16_f32 v200, v156, v157
	v_cvt_pk_bf16_f32 v201, v158, v159
	v_cvt_pk_bf16_f32 v202, v160, v161
	v_cvt_pk_bf16_f32 v203, v162, v163
	global_store_dwordx4 v23, v[196:199], s[30:31]
	global_store_dwordx4 v23, v[200:203], s[30:31] offset:1024
	v_mul_f32_e32 v164, v164, v215
	v_mul_f32_e32 v165, v165, v215
	v_mul_f32_e32 v166, v166, v215
	v_mul_f32_e32 v167, v167, v215
	v_mul_f32_e32 v168, v168, v215
	v_mul_f32_e32 v169, v169, v215
	v_mul_f32_e32 v170, v170, v215
	v_mul_f32_e32 v171, v171, v215
	v_mul_f32_e32 v172, v172, v215
	v_mul_f32_e32 v173, v173, v215
	v_mul_f32_e32 v174, v174, v215
	v_mul_f32_e32 v175, v175, v215
	v_mul_f32_e32 v176, v176, v215
	v_mul_f32_e32 v177, v177, v215
	v_mul_f32_e32 v178, v178, v215
	v_mul_f32_e32 v179, v179, v215
	v_mul_f32_e32 v164, v100, v164
	v_mul_f32_e32 v165, v101, v165
	v_mul_f32_e32 v166, v102, v166
	v_mul_f32_e32 v167, v103, v167
	v_mul_f32_e32 v168, v104, v168
	v_mul_f32_e32 v169, v105, v169
	v_mul_f32_e32 v170, v106, v170
	v_mul_f32_e32 v171, v107, v171
	v_mul_f32_e32 v172, v108, v172
	v_mul_f32_e32 v173, v109, v173
	v_mul_f32_e32 v174, v110, v174
	v_mul_f32_e32 v175, v111, v175
	v_mul_f32_e32 v176, v112, v176
	v_mul_f32_e32 v177, v113, v177
	v_mul_f32_e32 v178, v114, v178
	v_mul_f32_e32 v179, v115, v179
	v_cvt_pk_bf16_f32 v204, v164, v165
	v_cvt_pk_bf16_f32 v205, v166, v167
	v_cvt_pk_bf16_f32 v206, v168, v169
	v_cvt_pk_bf16_f32 v207, v170, v171
	v_cvt_pk_bf16_f32 v208, v172, v173
	v_cvt_pk_bf16_f32 v209, v174, v175
	v_cvt_pk_bf16_f32 v210, v176, v177
	v_cvt_pk_bf16_f32 v211, v178, v179
	global_store_dwordx4 v23, v[204:207], s[30:31] offset:2048
	global_store_dwordx4 v23, v[208:211], s[30:31] offset:3072
	s_branch .Lrms_done
.Lrms_loop1:
	s_add_i32 s17, s16, s54
	s_cmp_lt_u32 s17, s5
	s_cbranch_scc0 .Lrms_last1
	s_lshl_b32 s6, s17, 12
	s_add_u32 s18, s12, s6
	s_addc_u32 s19, s13, 0
	s_add_u32 s20, s18, 0x1000
	s_addc_u32 s21, s19, 0
	s_add_u32 s22, s20, 0x1000
	s_addc_u32 s23, s21, 0
	s_add_u32 s24, s22, 0x1000
	s_addc_u32 s25, s23, 0
	global_load_dwordx4 v[116:119], v22, s[18:19]
	global_load_dwordx4 v[120:123], v22, s[18:19] offset:16
	global_load_dwordx4 v[124:127], v22, s[18:19] offset:2048
	global_load_dwordx4 v[128:131], v22, s[18:19] offset:2064
	global_load_dwordx4 v[132:135], v22, s[20:21]
	global_load_dwordx4 v[136:139], v22, s[20:21] offset:16
	global_load_dwordx4 v[140:143], v22, s[20:21] offset:2048
	global_load_dwordx4 v[144:147], v22, s[20:21] offset:2064
	global_load_dwordx4 v[148:151], v22, s[22:23]
	global_load_dwordx4 v[152:155], v22, s[22:23] offset:16
	global_load_dwordx4 v[156:159], v22, s[22:23] offset:2048
	global_load_dwordx4 v[160:163], v22, s[22:23] offset:2064
	global_load_dwordx4 v[164:167], v22, s[24:25]
	global_load_dwordx4 v[168:171], v22, s[24:25] offset:16
	global_load_dwordx4 v[172:175], v22, s[24:25] offset:2048
	global_load_dwordx4 v[176:179], v22, s[24:25] offset:2064
	s_waitcnt vmcnt(24)
	v_mul_f32_e32 v8, v24, v24
	v_mul_f32_e32 v9, v40, v40
	v_mul_f32_e32 v10, v56, v56
	v_mul_f32_e32 v11, v72, v72
	v_fmac_f32_e32 v8, v25, v25
	v_fmac_f32_e32 v9, v41, v41
	v_fmac_f32_e32 v10, v57, v57
	v_fmac_f32_e32 v11, v73, v73
	v_fmac_f32_e32 v8, v26, v26
	v_fmac_f32_e32 v9, v42, v42
	v_fmac_f32_e32 v10, v58, v58
	v_fmac_f32_e32 v11, v74, v74
	v_fmac_f32_e32 v8, v27, v27
	v_fmac_f32_e32 v9, v43, v43
	v_fmac_f32_e32 v10, v59, v59
	v_fmac_f32_e32 v11, v75, v75
	v_fmac_f32_e32 v8, v28, v28
	v_fmac_f32_e32 v9, v44, v44
	v_fmac_f32_e32 v10, v60, v60
	v_fmac_f32_e32 v11, v76, v76
	v_fmac_f32_e32 v8, v29, v29
	v_fmac_f32_e32 v9, v45, v45
	v_fmac_f32_e32 v10, v61, v61
	v_fmac_f32_e32 v11, v77, v77
	v_fmac_f32_e32 v8, v30, v30
	v_fmac_f32_e32 v9, v46, v46
	v_fmac_f32_e32 v10, v62, v62
	v_fmac_f32_e32 v11, v78, v78
	v_fmac_f32_e32 v8, v31, v31
	v_fmac_f32_e32 v9, v47, v47
	v_fmac_f32_e32 v10, v63, v63
	v_fmac_f32_e32 v11, v79, v79
	v_fmac_f32_e32 v8, v32, v32
	v_fmac_f32_e32 v9, v48, v48
	v_fmac_f32_e32 v10, v64, v64
	v_fmac_f32_e32 v11, v80, v80
	v_fmac_f32_e32 v8, v33, v33
	v_fmac_f32_e32 v9, v49, v49
	v_fmac_f32_e32 v10, v65, v65
	v_fmac_f32_e32 v11, v81, v81
	v_fmac_f32_e32 v8, v34, v34
	v_fmac_f32_e32 v9, v50, v50
	v_fmac_f32_e32 v10, v66, v66
	v_fmac_f32_e32 v11, v82, v82
	v_fmac_f32_e32 v8, v35, v35
	v_fmac_f32_e32 v9, v51, v51
	v_fmac_f32_e32 v10, v67, v67
	v_fmac_f32_e32 v11, v83, v83
	v_fmac_f32_e32 v8, v36, v36
	v_fmac_f32_e32 v9, v52, v52
	v_fmac_f32_e32 v10, v68, v68
	v_fmac_f32_e32 v11, v84, v84
	v_fmac_f32_e32 v8, v37, v37
	v_fmac_f32_e32 v9, v53, v53
	v_fmac_f32_e32 v10, v69, v69
	v_fmac_f32_e32 v11, v85, v85
	v_fmac_f32_e32 v8, v38, v38
	v_fmac_f32_e32 v9, v54, v54
	v_fmac_f32_e32 v10, v70, v70
	v_fmac_f32_e32 v11, v86, v86
	v_fmac_f32_e32 v8, v39, v39
	v_fmac_f32_e32 v9, v55, v55
	v_fmac_f32_e32 v10, v71, v71
	v_fmac_f32_e32 v11, v87, v87
	ds_bpermute_b32 v12, v16, v8
	ds_bpermute_b32 v13, v16, v9
	ds_bpermute_b32 v14, v16, v10
	ds_bpermute_b32 v15, v16, v11
	s_waitcnt lgkmcnt(0)
	v_add_f32_e32 v8, v8, v12
	v_add_f32_e32 v9, v9, v13
	v_add_f32_e32 v10, v10, v14
	v_add_f32_e32 v11, v11, v15
	ds_bpermute_b32 v12, v17, v8
	ds_bpermute_b32 v13, v17, v9
	ds_bpermute_b32 v14, v17, v10
	ds_bpermute_b32 v15, v17, v11
	s_waitcnt lgkmcnt(0)
	v_add_f32_e32 v8, v8, v12
	v_add_f32_e32 v9, v9, v13
	v_add_f32_e32 v10, v10, v14
	v_add_f32_e32 v11, v11, v15
	ds_bpermute_b32 v12, v18, v8
	ds_bpermute_b32 v13, v18, v9
	ds_bpermute_b32 v14, v18, v10
	ds_bpermute_b32 v15, v18, v11
	s_waitcnt lgkmcnt(0)
	v_add_f32_e32 v8, v8, v12
	v_add_f32_e32 v9, v9, v13
	v_add_f32_e32 v10, v10, v14
	v_add_f32_e32 v11, v11, v15
	ds_bpermute_b32 v12, v19, v8
	ds_bpermute_b32 v13, v19, v9
	ds_bpermute_b32 v14, v19, v10
	ds_bpermute_b32 v15, v19, v11
	s_waitcnt lgkmcnt(0)
	v_add_f32_e32 v8, v8, v12
	v_add_f32_e32 v9, v9, v13
	v_add_f32_e32 v10, v10, v14
	v_add_f32_e32 v11, v11, v15
	ds_bpermute_b32 v12, v20, v8
	ds_bpermute_b32 v13, v20, v9
	ds_bpermute_b32 v14, v20, v10
	ds_bpermute_b32 v15, v20, v11
	s_waitcnt lgkmcnt(0)
	v_add_f32_e32 v8, v8, v12
	v_add_f32_e32 v9, v9, v13
	v_add_f32_e32 v10, v10, v14
	v_add_f32_e32 v11, v11, v15
	ds_bpermute_b32 v12, v21, v8
	ds_bpermute_b32 v13, v21, v9
	ds_bpermute_b32 v14, v21, v10
	ds_bpermute_b32 v15, v21, v11
	s_waitcnt lgkmcnt(0)
	v_add_f32_e32 v8, v8, v12
	v_add_f32_e32 v9, v9, v13
	v_add_f32_e32 v10, v10, v14
	v_add_f32_e32 v11, v11, v15
	v_fmamk_f32 v8, v8, 0x3a800000, v220
	v_fmamk_f32 v9, v9, 0x3a800000, v220
	v_fmamk_f32 v10, v10, 0x3a800000, v220
	v_fmamk_f32 v11, v11, 0x3a800000, v220
	v_mul_f32_e32 v12, 0x4b800000, v8
	v_mul_f32_e32 v13, 0x4b800000, v9
	v_mul_f32_e32 v14, 0x4b800000, v10
	v_mul_f32_e32 v15, 0x4b800000, v11
	v_cmp_gt_f32_e32 vcc, s7, v8
	s_nop 1
	v_cndmask_b32_e32 v8, v8, v12, vcc
	v_rsq_f32_e32 v212, v8
	s_nop 0
	v_mul_f32_e32 v216, 0x45800000, v212
	v_cndmask_b32_e32 v212, v212, v216, vcc
	v_cmp_gt_f32_e32 vcc, s7, v9
	s_nop 1
	v_cndmask_b32_e32 v9, v9, v13, vcc
	v_rsq_f32_e32 v213, v9
	s_nop 0
	v_mul_f32_e32 v216, 0x45800000, v213
	v_cndmask_b32_e32 v213, v213, v216, vcc
	v_cmp_gt_f32_e32 vcc, s7, v10
	s_nop 1
	v_cndmask_b32_e32 v10, v10, v14, vcc
	v_rsq_f32_e32 v214, v10
	s_nop 0
	v_mul_f32_e32 v216, 0x45800000, v214
	v_cndmask_b32_e32 v214, v214, v216, vcc
	v_cmp_gt_f32_e32 vcc, s7, v11
	s_nop 1
	v_cndmask_b32_e32 v11, v11, v15, vcc
	v_rsq_f32_e32 v215, v11
	s_nop 0
	v_mul_f32_e32 v216, 0x45800000, v215
	v_cndmask_b32_e32 v215, v215, v216, vcc
	s_lshl_b32 s6, s16, 11
	s_add_u32 s26, s46, s6
	s_addc_u32 s27, s47, 0
	s_add_u32 s30, s26, 0x1000
	s_addc_u32 s31, s27, 0
	v_mul_f32_e32 v24, v24, v212
	v_mul_f32_e32 v25, v25, v212
	v_mul_f32_e32 v26, v26, v212
	v_mul_f32_e32 v27, v27, v212
	v_mul_f32_e32 v28, v28, v212
	v_mul_f32_e32 v29, v29, v212
	v_mul_f32_e32 v30, v30, v212
	v_mul_f32_e32 v31, v31, v212
	v_mul_f32_e32 v32, v32, v212
	v_mul_f32_e32 v33, v33, v212
	v_mul_f32_e32 v34, v34, v212
	v_mul_f32_e32 v35, v35, v212
	v_mul_f32_e32 v36, v36, v212
	v_mul_f32_e32 v37, v37, v212
	v_mul_f32_e32 v38, v38, v212
	v_mul_f32_e32 v39, v39, v212
	v_mul_f32_e32 v24, v100, v24
	v_mul_f32_e32 v25, v101, v25
	v_mul_f32_e32 v26, v102, v26
	v_mul_f32_e32 v27, v103, v27
	v_mul_f32_e32 v28, v104, v28
	v_mul_f32_e32 v29, v105, v29
	v_mul_f32_e32 v30, v106, v30
	v_mul_f32_e32 v31, v107, v31
	v_mul_f32_e32 v32, v108, v32
	v_mul_f32_e32 v33, v109, v33
	v_mul_f32_e32 v34, v110, v34
	v_mul_f32_e32 v35, v111, v35
	v_mul_f32_e32 v36, v112, v36
	v_mul_f32_e32 v37, v113, v37
	v_mul_f32_e32 v38, v114, v38
	v_mul_f32_e32 v39, v115, v39
	v_cvt_pk_bf16_f32 v180, v24, v25
	v_cvt_pk_bf16_f32 v181, v26, v27
	v_cvt_pk_bf16_f32 v182, v28, v29
	v_cvt_pk_bf16_f32 v183, v30, v31
	v_cvt_pk_bf16_f32 v184, v32, v33
	v_cvt_pk_bf16_f32 v185, v34, v35
	v_cvt_pk_bf16_f32 v186, v36, v37
	v_cvt_pk_bf16_f32 v187, v38, v39
	global_store_dwordx4 v23, v[180:183], s[26:27]
	global_store_dwordx4 v23, v[184:187], s[26:27] offset:1024
	v_mul_f32_e32 v40, v40, v213
	v_mul_f32_e32 v41, v41, v213
	v_mul_f32_e32 v42, v42, v213
	v_mul_f32_e32 v43, v43, v213
	v_mul_f32_e32 v44, v44, v213
	v_mul_f32_e32 v45, v45, v213
	v_mul_f32_e32 v46, v46, v213
	v_mul_f32_e32 v47, v47, v213
	v_mul_f32_e32 v48, v48, v213
	v_mul_f32_e32 v49, v49, v213
	v_mul_f32_e32 v50, v50, v213
	v_mul_f32_e32 v51, v51, v213
	v_mul_f32_e32 v52, v52, v213
	v_mul_f32_e32 v53, v53, v213
	v_mul_f32_e32 v54, v54, v213
	v_mul_f32_e32 v55, v55, v213
	v_mul_f32_e32 v40, v100, v40
	v_mul_f32_e32 v41, v101, v41
	v_mul_f32_e32 v42, v102, v42
	v_mul_f32_e32 v43, v103, v43
	v_mul_f32_e32 v44, v104, v44
	v_mul_f32_e32 v45, v105, v45
	v_mul_f32_e32 v46, v106, v46
	v_mul_f32_e32 v47, v107, v47
	v_mul_f32_e32 v48, v108, v48
	v_mul_f32_e32 v49, v109, v49
	v_mul_f32_e32 v50, v110, v50
	v_mul_f32_e32 v51, v111, v51
	v_mul_f32_e32 v52, v112, v52
	v_mul_f32_e32 v53, v113, v53
	v_mul_f32_e32 v54, v114, v54
	v_mul_f32_e32 v55, v115, v55
	v_cvt_pk_bf16_f32 v188, v40, v41
	v_cvt_pk_bf16_f32 v189, v42, v43
	v_cvt_pk_bf16_f32 v190, v44, v45
	v_cvt_pk_bf16_f32 v191, v46, v47
	v_cvt_pk_bf16_f32 v192, v48, v49
	v_cvt_pk_bf16_f32 v193, v50, v51
	v_cvt_pk_bf16_f32 v194, v52, v53
	v_cvt_pk_bf16_f32 v195, v54, v55
	global_store_dwordx4 v23, v[188:191], s[26:27] offset:2048
	global_store_dwordx4 v23, v[192:195], s[26:27] offset:3072
	v_mul_f32_e32 v56, v56, v214
	v_mul_f32_e32 v57, v57, v214
	v_mul_f32_e32 v58, v58, v214
	v_mul_f32_e32 v59, v59, v214
	v_mul_f32_e32 v60, v60, v214
	v_mul_f32_e32 v61, v61, v214
	v_mul_f32_e32 v62, v62, v214
	v_mul_f32_e32 v63, v63, v214
	v_mul_f32_e32 v64, v64, v214
	v_mul_f32_e32 v65, v65, v214
	v_mul_f32_e32 v66, v66, v214
	v_mul_f32_e32 v67, v67, v214
	v_mul_f32_e32 v68, v68, v214
	v_mul_f32_e32 v69, v69, v214
	v_mul_f32_e32 v70, v70, v214
	v_mul_f32_e32 v71, v71, v214
	v_mul_f32_e32 v56, v100, v56
	v_mul_f32_e32 v57, v101, v57
	v_mul_f32_e32 v58, v102, v58
	v_mul_f32_e32 v59, v103, v59
	v_mul_f32_e32 v60, v104, v60
	v_mul_f32_e32 v61, v105, v61
	v_mul_f32_e32 v62, v106, v62
	v_mul_f32_e32 v63, v107, v63
	v_mul_f32_e32 v64, v108, v64
	v_mul_f32_e32 v65, v109, v65
	v_mul_f32_e32 v66, v110, v66
	v_mul_f32_e32 v67, v111, v67
	v_mul_f32_e32 v68, v112, v68
	v_mul_f32_e32 v69, v113, v69
	v_mul_f32_e32 v70, v114, v70
	v_mul_f32_e32 v71, v115, v71
	v_cvt_pk_bf16_f32 v196, v56, v57
	v_cvt_pk_bf16_f32 v197, v58, v59
	v_cvt_pk_bf16_f32 v198, v60, v61
	v_cvt_pk_bf16_f32 v199, v62, v63
	v_cvt_pk_bf16_f32 v200, v64, v65
	v_cvt_pk_bf16_f32 v201, v66, v67
	v_cvt_pk_bf16_f32 v202, v68, v69
	v_cvt_pk_bf16_f32 v203, v70, v71
	global_store_dwordx4 v23, v[196:199], s[30:31]
	global_store_dwordx4 v23, v[200:203], s[30:31] offset:1024
	v_mul_f32_e32 v72, v72, v215
	v_mul_f32_e32 v73, v73, v215
	v_mul_f32_e32 v74, v74, v215
	v_mul_f32_e32 v75, v75, v215
	v_mul_f32_e32 v76, v76, v215
	v_mul_f32_e32 v77, v77, v215
	v_mul_f32_e32 v78, v78, v215
	v_mul_f32_e32 v79, v79, v215
	v_mul_f32_e32 v80, v80, v215
	v_mul_f32_e32 v81, v81, v215
	v_mul_f32_e32 v82, v82, v215
	v_mul_f32_e32 v83, v83, v215
	v_mul_f32_e32 v84, v84, v215
	v_mul_f32_e32 v85, v85, v215
	v_mul_f32_e32 v86, v86, v215
	v_mul_f32_e32 v87, v87, v215
	v_mul_f32_e32 v72, v100, v72
	v_mul_f32_e32 v73, v101, v73
	v_mul_f32_e32 v74, v102, v74
	v_mul_f32_e32 v75, v103, v75
	v_mul_f32_e32 v76, v104, v76
	v_mul_f32_e32 v77, v105, v77
	v_mul_f32_e32 v78, v106, v78
	v_mul_f32_e32 v79, v107, v79
	v_mul_f32_e32 v80, v108, v80
	v_mul_f32_e32 v81, v109, v81
	v_mul_f32_e32 v82, v110, v82
	v_mul_f32_e32 v83, v111, v83
	v_mul_f32_e32 v84, v112, v84
	v_mul_f32_e32 v85, v113, v85
	v_mul_f32_e32 v86, v114, v86
	v_mul_f32_e32 v87, v115, v87
	v_cvt_pk_bf16_f32 v204, v72, v73
	v_cvt_pk_bf16_f32 v205, v74, v75
	v_cvt_pk_bf16_f32 v206, v76, v77
	v_cvt_pk_bf16_f32 v207, v78, v79
	v_cvt_pk_bf16_f32 v208, v80, v81
	v_cvt_pk_bf16_f32 v209, v82, v83
	v_cvt_pk_bf16_f32 v210, v84, v85
	v_cvt_pk_bf16_f32 v211, v86, v87
	global_store_dwordx4 v23, v[204:207], s[30:31] offset:2048
	global_store_dwordx4 v23, v[208:211], s[30:31] offset:3072
	s_mov_b32 s16, s17
	s_branch .Lrms_loop0
.Lrms_last1:
	s_waitcnt vmcnt(8)
	v_mul_f32_e32 v8, v24, v24
	v_mul_f32_e32 v9, v40, v40
	v_mul_f32_e32 v10, v56, v56
	v_mul_f32_e32 v11, v72, v72
	v_fmac_f32_e32 v8, v25, v25
	v_fmac_f32_e32 v9, v41, v41
	v_fmac_f32_e32 v10, v57, v57
	v_fmac_f32_e32 v11, v73, v73
	v_fmac_f32_e32 v8, v26, v26
	v_fmac_f32_e32 v9, v42, v42
	v_fmac_f32_e32 v10, v58, v58
	v_fmac_f32_e32 v11, v74, v74
	v_fmac_f32_e32 v8, v27, v27
	v_fmac_f32_e32 v9, v43, v43
	v_fmac_f32_e32 v10, v59, v59
	v_fmac_f32_e32 v11, v75, v75
	v_fmac_f32_e32 v8, v28, v28
	v_fmac_f32_e32 v9, v44, v44
	v_fmac_f32_e32 v10, v60, v60
	v_fmac_f32_e32 v11, v76, v76
	v_fmac_f32_e32 v8, v29, v29
	v_fmac_f32_e32 v9, v45, v45
	v_fmac_f32_e32 v10, v61, v61
	v_fmac_f32_e32 v11, v77, v77
	v_fmac_f32_e32 v8, v30, v30
	v_fmac_f32_e32 v9, v46, v46
	v_fmac_f32_e32 v10, v62, v62
	v_fmac_f32_e32 v11, v78, v78
	v_fmac_f32_e32 v8, v31, v31
	v_fmac_f32_e32 v9, v47, v47
	v_fmac_f32_e32 v10, v63, v63
	v_fmac_f32_e32 v11, v79, v79
	v_fmac_f32_e32 v8, v32, v32
	v_fmac_f32_e32 v9, v48, v48
	v_fmac_f32_e32 v10, v64, v64
	v_fmac_f32_e32 v11, v80, v80
	v_fmac_f32_e32 v8, v33, v33
	v_fmac_f32_e32 v9, v49, v49
	v_fmac_f32_e32 v10, v65, v65
	v_fmac_f32_e32 v11, v81, v81
	v_fmac_f32_e32 v8, v34, v34
	v_fmac_f32_e32 v9, v50, v50
	v_fmac_f32_e32 v10, v66, v66
	v_fmac_f32_e32 v11, v82, v82
	v_fmac_f32_e32 v8, v35, v35
	v_fmac_f32_e32 v9, v51, v51
	v_fmac_f32_e32 v10, v67, v67
	v_fmac_f32_e32 v11, v83, v83
	v_fmac_f32_e32 v8, v36, v36
	v_fmac_f32_e32 v9, v52, v52
	v_fmac_f32_e32 v10, v68, v68
	v_fmac_f32_e32 v11, v84, v84
	v_fmac_f32_e32 v8, v37, v37
	v_fmac_f32_e32 v9, v53, v53
	v_fmac_f32_e32 v10, v69, v69
	v_fmac_f32_e32 v11, v85, v85
	v_fmac_f32_e32 v8, v38, v38
	v_fmac_f32_e32 v9, v54, v54
	v_fmac_f32_e32 v10, v70, v70
	v_fmac_f32_e32 v11, v86, v86
	v_fmac_f32_e32 v8, v39, v39
	v_fmac_f32_e32 v9, v55, v55
	v_fmac_f32_e32 v10, v71, v71
	v_fmac_f32_e32 v11, v87, v87
	ds_bpermute_b32 v12, v16, v8
	ds_bpermute_b32 v13, v16, v9
	ds_bpermute_b32 v14, v16, v10
	ds_bpermute_b32 v15, v16, v11
	s_waitcnt lgkmcnt(0)
	v_add_f32_e32 v8, v8, v12
	v_add_f32_e32 v9, v9, v13
	v_add_f32_e32 v10, v10, v14
	v_add_f32_e32 v11, v11, v15
	ds_bpermute_b32 v12, v17, v8
	ds_bpermute_b32 v13, v17, v9
	ds_bpermute_b32 v14, v17, v10
	ds_bpermute_b32 v15, v17, v11
	s_waitcnt lgkmcnt(0)
	v_add_f32_e32 v8, v8, v12
	v_add_f32_e32 v9, v9, v13
	v_add_f32_e32 v10, v10, v14
	v_add_f32_e32 v11, v11, v15
	ds_bpermute_b32 v12, v18, v8
	ds_bpermute_b32 v13, v18, v9
	ds_bpermute_b32 v14, v18, v10
	ds_bpermute_b32 v15, v18, v11
	s_waitcnt lgkmcnt(0)
	v_add_f32_e32 v8, v8, v12
	v_add_f32_e32 v9, v9, v13
	v_add_f32_e32 v10, v10, v14
	v_add_f32_e32 v11, v11, v15
	ds_bpermute_b32 v12, v19, v8
	ds_bpermute_b32 v13, v19, v9
	ds_bpermute_b32 v14, v19, v10
	ds_bpermute_b32 v15, v19, v11
	s_waitcnt lgkmcnt(0)
	v_add_f32_e32 v8, v8, v12
	v_add_f32_e32 v9, v9, v13
	v_add_f32_e32 v10, v10, v14
	v_add_f32_e32 v11, v11, v15
	ds_bpermute_b32 v12, v20, v8
	ds_bpermute_b32 v13, v20, v9
	ds_bpermute_b32 v14, v20, v10
	ds_bpermute_b32 v15, v20, v11
	s_waitcnt lgkmcnt(0)
	v_add_f32_e32 v8, v8, v12
	v_add_f32_e32 v9, v9, v13
	v_add_f32_e32 v10, v10, v14
	v_add_f32_e32 v11, v11, v15
	ds_bpermute_b32 v12, v21, v8
	ds_bpermute_b32 v13, v21, v9
	ds_bpermute_b32 v14, v21, v10
	ds_bpermute_b32 v15, v21, v11
	s_waitcnt lgkmcnt(0)
	v_add_f32_e32 v8, v8, v12
	v_add_f32_e32 v9, v9, v13
	v_add_f32_e32 v10, v10, v14
	v_add_f32_e32 v11, v11, v15
	v_fmamk_f32 v8, v8, 0x3a800000, v220
	v_fmamk_f32 v9, v9, 0x3a800000, v220
	v_fmamk_f32 v10, v10, 0x3a800000, v220
	v_fmamk_f32 v11, v11, 0x3a800000, v220
	v_mul_f32_e32 v12, 0x4b800000, v8
	v_mul_f32_e32 v13, 0x4b800000, v9
	v_mul_f32_e32 v14, 0x4b800000, v10
	v_mul_f32_e32 v15, 0x4b800000, v11
	v_cmp_gt_f32_e32 vcc, s7, v8
	s_nop 1
	v_cndmask_b32_e32 v8, v8, v12, vcc
	v_rsq_f32_e32 v212, v8
	s_nop 0
	v_mul_f32_e32 v216, 0x45800000, v212
	v_cndmask_b32_e32 v212, v212, v216, vcc
	v_cmp_gt_f32_e32 vcc, s7, v9
	s_nop 1
	v_cndmask_b32_e32 v9, v9, v13, vcc
	v_rsq_f32_e32 v213, v9
	s_nop 0
	v_mul_f32_e32 v216, 0x45800000, v213
	v_cndmask_b32_e32 v213, v213, v216, vcc
	v_cmp_gt_f32_e32 vcc, s7, v10
	s_nop 1
	v_cndmask_b32_e32 v10, v10, v14, vcc
	v_rsq_f32_e32 v214, v10
	s_nop 0
	v_mul_f32_e32 v216, 0x45800000, v214
	v_cndmask_b32_e32 v214, v214, v216, vcc
	v_cmp_gt_f32_e32 vcc, s7, v11
	s_nop 1
	v_cndmask_b32_e32 v11, v11, v15, vcc
	v_rsq_f32_e32 v215, v11
	s_nop 0
	v_mul_f32_e32 v216, 0x45800000, v215
	v_cndmask_b32_e32 v215, v215, v216, vcc
	s_lshl_b32 s6, s16, 11
	s_add_u32 s26, s46, s6
	s_addc_u32 s27, s47, 0
	s_add_u32 s30, s26, 0x1000
	s_addc_u32 s31, s27, 0
	v_mul_f32_e32 v24, v24, v212
	v_mul_f32_e32 v25, v25, v212
	v_mul_f32_e32 v26, v26, v212
	v_mul_f32_e32 v27, v27, v212
	v_mul_f32_e32 v28, v28, v212
	v_mul_f32_e32 v29, v29, v212
	v_mul_f32_e32 v30, v30, v212
	v_mul_f32_e32 v31, v31, v212
	v_mul_f32_e32 v32, v32, v212
	v_mul_f32_e32 v33, v33, v212
	v_mul_f32_e32 v34, v34, v212
	v_mul_f32_e32 v35, v35, v212
	v_mul_f32_e32 v36, v36, v212
	v_mul_f32_e32 v37, v37, v212
	v_mul_f32_e32 v38, v38, v212
	v_mul_f32_e32 v39, v39, v212
	v_mul_f32_e32 v24, v100, v24
	v_mul_f32_e32 v25, v101, v25
	v_mul_f32_e32 v26, v102, v26
	v_mul_f32_e32 v27, v103, v27
	v_mul_f32_e32 v28, v104, v28
	v_mul_f32_e32 v29, v105, v29
	v_mul_f32_e32 v30, v106, v30
	v_mul_f32_e32 v31, v107, v31
	v_mul_f32_e32 v32, v108, v32
	v_mul_f32_e32 v33, v109, v33
	v_mul_f32_e32 v34, v110, v34
	v_mul_f32_e32 v35, v111, v35
	v_mul_f32_e32 v36, v112, v36
	v_mul_f32_e32 v37, v113, v37
	v_mul_f32_e32 v38, v114, v38
	v_mul_f32_e32 v39, v115, v39
	v_cvt_pk_bf16_f32 v180, v24, v25
	v_cvt_pk_bf16_f32 v181, v26, v27
	v_cvt_pk_bf16_f32 v182, v28, v29
	v_cvt_pk_bf16_f32 v183, v30, v31
	v_cvt_pk_bf16_f32 v184, v32, v33
	v_cvt_pk_bf16_f32 v185, v34, v35
	v_cvt_pk_bf16_f32 v186, v36, v37
	v_cvt_pk_bf16_f32 v187, v38, v39
	global_store_dwordx4 v23, v[180:183], s[26:27]
	global_store_dwordx4 v23, v[184:187], s[26:27] offset:1024
	v_mul_f32_e32 v40, v40, v213
	v_mul_f32_e32 v41, v41, v213
	v_mul_f32_e32 v42, v42, v213
	v_mul_f32_e32 v43, v43, v213
	v_mul_f32_e32 v44, v44, v213
	v_mul_f32_e32 v45, v45, v213
	v_mul_f32_e32 v46, v46, v213
	v_mul_f32_e32 v47, v47, v213
	v_mul_f32_e32 v48, v48, v213
	v_mul_f32_e32 v49, v49, v213
	v_mul_f32_e32 v50, v50, v213
	v_mul_f32_e32 v51, v51, v213
	v_mul_f32_e32 v52, v52, v213
	v_mul_f32_e32 v53, v53, v213
	v_mul_f32_e32 v54, v54, v213
	v_mul_f32_e32 v55, v55, v213
	v_mul_f32_e32 v40, v100, v40
	v_mul_f32_e32 v41, v101, v41
	v_mul_f32_e32 v42, v102, v42
	v_mul_f32_e32 v43, v103, v43
	v_mul_f32_e32 v44, v104, v44
	v_mul_f32_e32 v45, v105, v45
	v_mul_f32_e32 v46, v106, v46
	v_mul_f32_e32 v47, v107, v47
	v_mul_f32_e32 v48, v108, v48
	v_mul_f32_e32 v49, v109, v49
	v_mul_f32_e32 v50, v110, v50
	v_mul_f32_e32 v51, v111, v51
	v_mul_f32_e32 v52, v112, v52
	v_mul_f32_e32 v53, v113, v53
	v_mul_f32_e32 v54, v114, v54
	v_mul_f32_e32 v55, v115, v55
	v_cvt_pk_bf16_f32 v188, v40, v41
	v_cvt_pk_bf16_f32 v189, v42, v43
	v_cvt_pk_bf16_f32 v190, v44, v45
	v_cvt_pk_bf16_f32 v191, v46, v47
	v_cvt_pk_bf16_f32 v192, v48, v49
	v_cvt_pk_bf16_f32 v193, v50, v51
	v_cvt_pk_bf16_f32 v194, v52, v53
	v_cvt_pk_bf16_f32 v195, v54, v55
	global_store_dwordx4 v23, v[188:191], s[26:27] offset:2048
	global_store_dwordx4 v23, v[192:195], s[26:27] offset:3072
	v_mul_f32_e32 v56, v56, v214
	v_mul_f32_e32 v57, v57, v214
	v_mul_f32_e32 v58, v58, v214
	v_mul_f32_e32 v59, v59, v214
	v_mul_f32_e32 v60, v60, v214
	v_mul_f32_e32 v61, v61, v214
	v_mul_f32_e32 v62, v62, v214
	v_mul_f32_e32 v63, v63, v214
	v_mul_f32_e32 v64, v64, v214
	v_mul_f32_e32 v65, v65, v214
	v_mul_f32_e32 v66, v66, v214
	v_mul_f32_e32 v67, v67, v214
	v_mul_f32_e32 v68, v68, v214
	v_mul_f32_e32 v69, v69, v214
	v_mul_f32_e32 v70, v70, v214
	v_mul_f32_e32 v71, v71, v214
	v_mul_f32_e32 v56, v100, v56
	v_mul_f32_e32 v57, v101, v57
	v_mul_f32_e32 v58, v102, v58
	v_mul_f32_e32 v59, v103, v59
	v_mul_f32_e32 v60, v104, v60
	v_mul_f32_e32 v61, v105, v61
	v_mul_f32_e32 v62, v106, v62
	v_mul_f32_e32 v63, v107, v63
	v_mul_f32_e32 v64, v108, v64
	v_mul_f32_e32 v65, v109, v65
	v_mul_f32_e32 v66, v110, v66
	v_mul_f32_e32 v67, v111, v67
	v_mul_f32_e32 v68, v112, v68
	v_mul_f32_e32 v69, v113, v69
	v_mul_f32_e32 v70, v114, v70
	v_mul_f32_e32 v71, v115, v71
	v_cvt_pk_bf16_f32 v196, v56, v57
	v_cvt_pk_bf16_f32 v197, v58, v59
	v_cvt_pk_bf16_f32 v198, v60, v61
	v_cvt_pk_bf16_f32 v199, v62, v63
	v_cvt_pk_bf16_f32 v200, v64, v65
	v_cvt_pk_bf16_f32 v201, v66, v67
	v_cvt_pk_bf16_f32 v202, v68, v69
	v_cvt_pk_bf16_f32 v203, v70, v71
	global_store_dwordx4 v23, v[196:199], s[30:31]
	global_store_dwordx4 v23, v[200:203], s[30:31] offset:1024
	v_mul_f32_e32 v72, v72, v215
	v_mul_f32_e32 v73, v73, v215
	v_mul_f32_e32 v74, v74, v215
	v_mul_f32_e32 v75, v75, v215
	v_mul_f32_e32 v76, v76, v215
	v_mul_f32_e32 v77, v77, v215
	v_mul_f32_e32 v78, v78, v215
	v_mul_f32_e32 v79, v79, v215
	v_mul_f32_e32 v80, v80, v215
	v_mul_f32_e32 v81, v81, v215
	v_mul_f32_e32 v82, v82, v215
	v_mul_f32_e32 v83, v83, v215
	v_mul_f32_e32 v84, v84, v215
	v_mul_f32_e32 v85, v85, v215
	v_mul_f32_e32 v86, v86, v215
	v_mul_f32_e32 v87, v87, v215
	v_mul_f32_e32 v72, v100, v72
	v_mul_f32_e32 v73, v101, v73
	v_mul_f32_e32 v74, v102, v74
	v_mul_f32_e32 v75, v103, v75
	v_mul_f32_e32 v76, v104, v76
	v_mul_f32_e32 v77, v105, v77
	v_mul_f32_e32 v78, v106, v78
	v_mul_f32_e32 v79, v107, v79
	v_mul_f32_e32 v80, v108, v80
	v_mul_f32_e32 v81, v109, v81
	v_mul_f32_e32 v82, v110, v82
	v_mul_f32_e32 v83, v111, v83
	v_mul_f32_e32 v84, v112, v84
	v_mul_f32_e32 v85, v113, v85
	v_mul_f32_e32 v86, v114, v86
	v_mul_f32_e32 v87, v115, v87
	v_cvt_pk_bf16_f32 v204, v72, v73
	v_cvt_pk_bf16_f32 v205, v74, v75
	v_cvt_pk_bf16_f32 v206, v76, v77
	v_cvt_pk_bf16_f32 v207, v78, v79
	v_cvt_pk_bf16_f32 v208, v80, v81
	v_cvt_pk_bf16_f32 v209, v82, v83
	v_cvt_pk_bf16_f32 v210, v84, v85
	v_cvt_pk_bf16_f32 v211, v86, v87
	global_store_dwordx4 v23, v[204:207], s[30:31] offset:2048
	global_store_dwordx4 v23, v[208:211], s[30:31] offset:3072
	s_branch .Lrms_done
.Lrms_loop0:
	s_add_i32 s17, s16, s54
	s_cmp_lt_u32 s17, s5
	s_cbranch_scc0 .Lrms_last0
	s_lshl_b32 s6, s17, 12
	s_add_u32 s18, s12, s6
	s_addc_u32 s19, s13, 0
	s_add_u32 s20, s18, 0x1000
	s_addc_u32 s21, s19, 0
	s_add_u32 s22, s20, 0x1000
	s_addc_u32 s23, s21, 0
	s_add_u32 s24, s22, 0x1000
	s_addc_u32 s25, s23, 0
	global_load_dwordx4 v[24:27], v22, s[18:19]
	global_load_dwordx4 v[28:31], v22, s[18:19] offset:16
	global_load_dwordx4 v[32:35], v22, s[18:19] offset:2048
	global_load_dwordx4 v[36:39], v22, s[18:19] offset:2064
	global_load_dwordx4 v[40:43], v22, s[20:21]
	global_load_dwordx4 v[44:47], v22, s[20:21] offset:16
	global_load_dwordx4 v[48:51], v22, s[20:21] offset:2048
	global_load_dwordx4 v[52:55], v22, s[20:21] offset:2064
	global_load_dwordx4 v[56:59], v22, s[22:23]
	global_load_dwordx4 v[60:63], v22, s[22:23] offset:16
	global_load_dwordx4 v[64:67], v22, s[22:23] offset:2048
	global_load_dwordx4 v[68:71], v22, s[22:23] offset:2064
	global_load_dwordx4 v[72:75], v22, s[24:25]
	global_load_dwordx4 v[76:79], v22, s[24:25] offset:16
	global_load_dwordx4 v[80:83], v22, s[24:25] offset:2048
	global_load_dwordx4 v[84:87], v22, s[24:25] offset:2064
	s_waitcnt vmcnt(24)
	v_mul_f32_e32 v8, v116, v116
	v_mul_f32_e32 v9, v132, v132
	v_mul_f32_e32 v10, v148, v148
	v_mul_f32_e32 v11, v164, v164
	v_fmac_f32_e32 v8, v117, v117
	v_fmac_f32_e32 v9, v133, v133
	v_fmac_f32_e32 v10, v149, v149
	v_fmac_f32_e32 v11, v165, v165
	v_fmac_f32_e32 v8, v118, v118
	v_fmac_f32_e32 v9, v134, v134
	v_fmac_f32_e32 v10, v150, v150
	v_fmac_f32_e32 v11, v166, v166
	v_fmac_f32_e32 v8, v119, v119
	v_fmac_f32_e32 v9, v135, v135
	v_fmac_f32_e32 v10, v151, v151
	v_fmac_f32_e32 v11, v167, v167
	v_fmac_f32_e32 v8, v120, v120
	v_fmac_f32_e32 v9, v136, v136
	v_fmac_f32_e32 v10, v152, v152
	v_fmac_f32_e32 v11, v168, v168
	v_fmac_f32_e32 v8, v121, v121
	v_fmac_f32_e32 v9, v137, v137
	v_fmac_f32_e32 v10, v153, v153
	v_fmac_f32_e32 v11, v169, v169
	v_fmac_f32_e32 v8, v122, v122
	v_fmac_f32_e32 v9, v138, v138
	v_fmac_f32_e32 v10, v154, v154
	v_fmac_f32_e32 v11, v170, v170
	v_fmac_f32_e32 v8, v123, v123
	v_fmac_f32_e32 v9, v139, v139
	v_fmac_f32_e32 v10, v155, v155
	v_fmac_f32_e32 v11, v171, v171
	v_fmac_f32_e32 v8, v124, v124
	v_fmac_f32_e32 v9, v140, v140
	v_fmac_f32_e32 v10, v156, v156
	v_fmac_f32_e32 v11, v172, v172
	v_fmac_f32_e32 v8, v125, v125
	v_fmac_f32_e32 v9, v141, v141
	v_fmac_f32_e32 v10, v157, v157
	v_fmac_f32_e32 v11, v173, v173
	v_fmac_f32_e32 v8, v126, v126
	v_fmac_f32_e32 v9, v142, v142
	v_fmac_f32_e32 v10, v158, v158
	v_fmac_f32_e32 v11, v174, v174
	v_fmac_f32_e32 v8, v127, v127
	v_fmac_f32_e32 v9, v143, v143
	v_fmac_f32_e32 v10, v159, v159
	v_fmac_f32_e32 v11, v175, v175
	v_fmac_f32_e32 v8, v128, v128
	v_fmac_f32_e32 v9, v144, v144
	v_fmac_f32_e32 v10, v160, v160
	v_fmac_f32_e32 v11, v176, v176
	v_fmac_f32_e32 v8, v129, v129
	v_fmac_f32_e32 v9, v145, v145
	v_fmac_f32_e32 v10, v161, v161
	v_fmac_f32_e32 v11, v177, v177
	v_fmac_f32_e32 v8, v130, v130
	v_fmac_f32_e32 v9, v146, v146
	v_fmac_f32_e32 v10, v162, v162
	v_fmac_f32_e32 v11, v178, v178
	v_fmac_f32_e32 v8, v131, v131
	v_fmac_f32_e32 v9, v147, v147
	v_fmac_f32_e32 v10, v163, v163
	v_fmac_f32_e32 v11, v179, v179
	ds_bpermute_b32 v12, v16, v8
	ds_bpermute_b32 v13, v16, v9
	ds_bpermute_b32 v14, v16, v10
	ds_bpermute_b32 v15, v16, v11
	s_waitcnt lgkmcnt(0)
	v_add_f32_e32 v8, v8, v12
	v_add_f32_e32 v9, v9, v13
	v_add_f32_e32 v10, v10, v14
	v_add_f32_e32 v11, v11, v15
	ds_bpermute_b32 v12, v17, v8
	ds_bpermute_b32 v13, v17, v9
	ds_bpermute_b32 v14, v17, v10
	ds_bpermute_b32 v15, v17, v11
	s_waitcnt lgkmcnt(0)
	v_add_f32_e32 v8, v8, v12
	v_add_f32_e32 v9, v9, v13
	v_add_f32_e32 v10, v10, v14
	v_add_f32_e32 v11, v11, v15
	ds_bpermute_b32 v12, v18, v8
	ds_bpermute_b32 v13, v18, v9
	ds_bpermute_b32 v14, v18, v10
	ds_bpermute_b32 v15, v18, v11
	s_waitcnt lgkmcnt(0)
	v_add_f32_e32 v8, v8, v12
	v_add_f32_e32 v9, v9, v13
	v_add_f32_e32 v10, v10, v14
	v_add_f32_e32 v11, v11, v15
	ds_bpermute_b32 v12, v19, v8
	ds_bpermute_b32 v13, v19, v9
	ds_bpermute_b32 v14, v19, v10
	ds_bpermute_b32 v15, v19, v11
	s_waitcnt lgkmcnt(0)
	v_add_f32_e32 v8, v8, v12
	v_add_f32_e32 v9, v9, v13
	v_add_f32_e32 v10, v10, v14
	v_add_f32_e32 v11, v11, v15
	ds_bpermute_b32 v12, v20, v8
	ds_bpermute_b32 v13, v20, v9
	ds_bpermute_b32 v14, v20, v10
	ds_bpermute_b32 v15, v20, v11
	s_waitcnt lgkmcnt(0)
	v_add_f32_e32 v8, v8, v12
	v_add_f32_e32 v9, v9, v13
	v_add_f32_e32 v10, v10, v14
	v_add_f32_e32 v11, v11, v15
	ds_bpermute_b32 v12, v21, v8
	ds_bpermute_b32 v13, v21, v9
	ds_bpermute_b32 v14, v21, v10
	ds_bpermute_b32 v15, v21, v11
	s_waitcnt lgkmcnt(0)
	v_add_f32_e32 v8, v8, v12
	v_add_f32_e32 v9, v9, v13
	v_add_f32_e32 v10, v10, v14
	v_add_f32_e32 v11, v11, v15
	v_fmamk_f32 v8, v8, 0x3a800000, v220
	v_fmamk_f32 v9, v9, 0x3a800000, v220
	v_fmamk_f32 v10, v10, 0x3a800000, v220
	v_fmamk_f32 v11, v11, 0x3a800000, v220
	v_mul_f32_e32 v12, 0x4b800000, v8
	v_mul_f32_e32 v13, 0x4b800000, v9
	v_mul_f32_e32 v14, 0x4b800000, v10
	v_mul_f32_e32 v15, 0x4b800000, v11
	v_cmp_gt_f32_e32 vcc, s7, v8
	s_nop 1
	v_cndmask_b32_e32 v8, v8, v12, vcc
	v_rsq_f32_e32 v212, v8
	s_nop 0
	v_mul_f32_e32 v216, 0x45800000, v212
	v_cndmask_b32_e32 v212, v212, v216, vcc
	v_cmp_gt_f32_e32 vcc, s7, v9
	s_nop 1
	v_cndmask_b32_e32 v9, v9, v13, vcc
	v_rsq_f32_e32 v213, v9
	s_nop 0
	v_mul_f32_e32 v216, 0x45800000, v213
	v_cndmask_b32_e32 v213, v213, v216, vcc
	v_cmp_gt_f32_e32 vcc, s7, v10
	s_nop 1
	v_cndmask_b32_e32 v10, v10, v14, vcc
	v_rsq_f32_e32 v214, v10
	s_nop 0
	v_mul_f32_e32 v216, 0x45800000, v214
	v_cndmask_b32_e32 v214, v214, v216, vcc
	v_cmp_gt_f32_e32 vcc, s7, v11
	s_nop 1
	v_cndmask_b32_e32 v11, v11, v15, vcc
	v_rsq_f32_e32 v215, v11
	s_nop 0
	v_mul_f32_e32 v216, 0x45800000, v215
	v_cndmask_b32_e32 v215, v215, v216, vcc
	s_lshl_b32 s6, s16, 11
	s_add_u32 s26, s46, s6
	s_addc_u32 s27, s47, 0
	s_add_u32 s30, s26, 0x1000
	s_addc_u32 s31, s27, 0
	v_mul_f32_e32 v116, v116, v212
	v_mul_f32_e32 v117, v117, v212
	v_mul_f32_e32 v118, v118, v212
	v_mul_f32_e32 v119, v119, v212
	v_mul_f32_e32 v120, v120, v212
	v_mul_f32_e32 v121, v121, v212
	v_mul_f32_e32 v122, v122, v212
	v_mul_f32_e32 v123, v123, v212
	v_mul_f32_e32 v124, v124, v212
	v_mul_f32_e32 v125, v125, v212
	v_mul_f32_e32 v126, v126, v212
	v_mul_f32_e32 v127, v127, v212
	v_mul_f32_e32 v128, v128, v212
	v_mul_f32_e32 v129, v129, v212
	v_mul_f32_e32 v130, v130, v212
	v_mul_f32_e32 v131, v131, v212
	v_mul_f32_e32 v116, v100, v116
	v_mul_f32_e32 v117, v101, v117
	v_mul_f32_e32 v118, v102, v118
	v_mul_f32_e32 v119, v103, v119
	v_mul_f32_e32 v120, v104, v120
	v_mul_f32_e32 v121, v105, v121
	v_mul_f32_e32 v122, v106, v122
	v_mul_f32_e32 v123, v107, v123
	v_mul_f32_e32 v124, v108, v124
	v_mul_f32_e32 v125, v109, v125
	v_mul_f32_e32 v126, v110, v126
	v_mul_f32_e32 v127, v111, v127
	v_mul_f32_e32 v128, v112, v128
	v_mul_f32_e32 v129, v113, v129
	v_mul_f32_e32 v130, v114, v130
	v_mul_f32_e32 v131, v115, v131
	v_cvt_pk_bf16_f32 v180, v116, v117
	v_cvt_pk_bf16_f32 v181, v118, v119
	v_cvt_pk_bf16_f32 v182, v120, v121
	v_cvt_pk_bf16_f32 v183, v122, v123
	v_cvt_pk_bf16_f32 v184, v124, v125
	v_cvt_pk_bf16_f32 v185, v126, v127
	v_cvt_pk_bf16_f32 v186, v128, v129
	v_cvt_pk_bf16_f32 v187, v130, v131
	global_store_dwordx4 v23, v[180:183], s[26:27]
	global_store_dwordx4 v23, v[184:187], s[26:27] offset:1024
	v_mul_f32_e32 v132, v132, v213
	v_mul_f32_e32 v133, v133, v213
	v_mul_f32_e32 v134, v134, v213
	v_mul_f32_e32 v135, v135, v213
	v_mul_f32_e32 v136, v136, v213
	v_mul_f32_e32 v137, v137, v213
	v_mul_f32_e32 v138, v138, v213
	v_mul_f32_e32 v139, v139, v213
	v_mul_f32_e32 v140, v140, v213
	v_mul_f32_e32 v141, v141, v213
	v_mul_f32_e32 v142, v142, v213
	v_mul_f32_e32 v143, v143, v213
	v_mul_f32_e32 v144, v144, v213
	v_mul_f32_e32 v145, v145, v213
	v_mul_f32_e32 v146, v146, v213
	v_mul_f32_e32 v147, v147, v213
	v_mul_f32_e32 v132, v100, v132
	v_mul_f32_e32 v133, v101, v133
	v_mul_f32_e32 v134, v102, v134
	v_mul_f32_e32 v135, v103, v135
	v_mul_f32_e32 v136, v104, v136
	v_mul_f32_e32 v137, v105, v137
	v_mul_f32_e32 v138, v106, v138
	v_mul_f32_e32 v139, v107, v139
	v_mul_f32_e32 v140, v108, v140
	v_mul_f32_e32 v141, v109, v141
	v_mul_f32_e32 v142, v110, v142
	v_mul_f32_e32 v143, v111, v143
	v_mul_f32_e32 v144, v112, v144
	v_mul_f32_e32 v145, v113, v145
	v_mul_f32_e32 v146, v114, v146
	v_mul_f32_e32 v147, v115, v147
	v_cvt_pk_bf16_f32 v188, v132, v133
	v_cvt_pk_bf16_f32 v189, v134, v135
	v_cvt_pk_bf16_f32 v190, v136, v137
	v_cvt_pk_bf16_f32 v191, v138, v139
	v_cvt_pk_bf16_f32 v192, v140, v141
	v_cvt_pk_bf16_f32 v193, v142, v143
	v_cvt_pk_bf16_f32 v194, v144, v145
	v_cvt_pk_bf16_f32 v195, v146, v147
	global_store_dwordx4 v23, v[188:191], s[26:27] offset:2048
	global_store_dwordx4 v23, v[192:195], s[26:27] offset:3072
	v_mul_f32_e32 v148, v148, v214
	v_mul_f32_e32 v149, v149, v214
	v_mul_f32_e32 v150, v150, v214
	v_mul_f32_e32 v151, v151, v214
	v_mul_f32_e32 v152, v152, v214
	v_mul_f32_e32 v153, v153, v214
	v_mul_f32_e32 v154, v154, v214
	v_mul_f32_e32 v155, v155, v214
	v_mul_f32_e32 v156, v156, v214
	v_mul_f32_e32 v157, v157, v214
	v_mul_f32_e32 v158, v158, v214
	v_mul_f32_e32 v159, v159, v214
	v_mul_f32_e32 v160, v160, v214
	v_mul_f32_e32 v161, v161, v214
	v_mul_f32_e32 v162, v162, v214
	v_mul_f32_e32 v163, v163, v214
	v_mul_f32_e32 v148, v100, v148
	v_mul_f32_e32 v149, v101, v149
	v_mul_f32_e32 v150, v102, v150
	v_mul_f32_e32 v151, v103, v151
	v_mul_f32_e32 v152, v104, v152
	v_mul_f32_e32 v153, v105, v153
	v_mul_f32_e32 v154, v106, v154
	v_mul_f32_e32 v155, v107, v155
	v_mul_f32_e32 v156, v108, v156
	v_mul_f32_e32 v157, v109, v157
	v_mul_f32_e32 v158, v110, v158
	v_mul_f32_e32 v159, v111, v159
	v_mul_f32_e32 v160, v112, v160
	v_mul_f32_e32 v161, v113, v161
	v_mul_f32_e32 v162, v114, v162
	v_mul_f32_e32 v163, v115, v163
	v_cvt_pk_bf16_f32 v196, v148, v149
	v_cvt_pk_bf16_f32 v197, v150, v151
	v_cvt_pk_bf16_f32 v198, v152, v153
	v_cvt_pk_bf16_f32 v199, v154, v155
	v_cvt_pk_bf16_f32 v200, v156, v157
	v_cvt_pk_bf16_f32 v201, v158, v159
	v_cvt_pk_bf16_f32 v202, v160, v161
	v_cvt_pk_bf16_f32 v203, v162, v163
	global_store_dwordx4 v23, v[196:199], s[30:31]
	global_store_dwordx4 v23, v[200:203], s[30:31] offset:1024
	v_mul_f32_e32 v164, v164, v215
	v_mul_f32_e32 v165, v165, v215
	v_mul_f32_e32 v166, v166, v215
	v_mul_f32_e32 v167, v167, v215
	v_mul_f32_e32 v168, v168, v215
	v_mul_f32_e32 v169, v169, v215
	v_mul_f32_e32 v170, v170, v215
	v_mul_f32_e32 v171, v171, v215
	v_mul_f32_e32 v172, v172, v215
	v_mul_f32_e32 v173, v173, v215
	v_mul_f32_e32 v174, v174, v215
	v_mul_f32_e32 v175, v175, v215
	v_mul_f32_e32 v176, v176, v215
	v_mul_f32_e32 v177, v177, v215
	v_mul_f32_e32 v178, v178, v215
	v_mul_f32_e32 v179, v179, v215
	v_mul_f32_e32 v164, v100, v164
	v_mul_f32_e32 v165, v101, v165
	v_mul_f32_e32 v166, v102, v166
	v_mul_f32_e32 v167, v103, v167
	v_mul_f32_e32 v168, v104, v168
	v_mul_f32_e32 v169, v105, v169
	v_mul_f32_e32 v170, v106, v170
	v_mul_f32_e32 v171, v107, v171
	v_mul_f32_e32 v172, v108, v172
	v_mul_f32_e32 v173, v109, v173
	v_mul_f32_e32 v174, v110, v174
	v_mul_f32_e32 v175, v111, v175
	v_mul_f32_e32 v176, v112, v176
	v_mul_f32_e32 v177, v113, v177
	v_mul_f32_e32 v178, v114, v178
	v_mul_f32_e32 v179, v115, v179
	v_cvt_pk_bf16_f32 v204, v164, v165
	v_cvt_pk_bf16_f32 v205, v166, v167
	v_cvt_pk_bf16_f32 v206, v168, v169
	v_cvt_pk_bf16_f32 v207, v170, v171
	v_cvt_pk_bf16_f32 v208, v172, v173
	v_cvt_pk_bf16_f32 v209, v174, v175
	v_cvt_pk_bf16_f32 v210, v176, v177
	v_cvt_pk_bf16_f32 v211, v178, v179
	global_store_dwordx4 v23, v[204:207], s[30:31] offset:2048
	global_store_dwordx4 v23, v[208:211], s[30:31] offset:3072
	s_mov_b32 s16, s17
	s_branch .Lrms_loop1
.Lrms_last0:
	s_waitcnt vmcnt(8)
	v_mul_f32_e32 v8, v116, v116
	v_mul_f32_e32 v9, v132, v132
	v_mul_f32_e32 v10, v148, v148
	v_mul_f32_e32 v11, v164, v164
	v_fmac_f32_e32 v8, v117, v117
	v_fmac_f32_e32 v9, v133, v133
	v_fmac_f32_e32 v10, v149, v149
	v_fmac_f32_e32 v11, v165, v165
	v_fmac_f32_e32 v8, v118, v118
	v_fmac_f32_e32 v9, v134, v134
	v_fmac_f32_e32 v10, v150, v150
	v_fmac_f32_e32 v11, v166, v166
	v_fmac_f32_e32 v8, v119, v119
	v_fmac_f32_e32 v9, v135, v135
	v_fmac_f32_e32 v10, v151, v151
	v_fmac_f32_e32 v11, v167, v167
	v_fmac_f32_e32 v8, v120, v120
	v_fmac_f32_e32 v9, v136, v136
	v_fmac_f32_e32 v10, v152, v152
	v_fmac_f32_e32 v11, v168, v168
	v_fmac_f32_e32 v8, v121, v121
	v_fmac_f32_e32 v9, v137, v137
	v_fmac_f32_e32 v10, v153, v153
	v_fmac_f32_e32 v11, v169, v169
	v_fmac_f32_e32 v8, v122, v122
	v_fmac_f32_e32 v9, v138, v138
	v_fmac_f32_e32 v10, v154, v154
	v_fmac_f32_e32 v11, v170, v170
	v_fmac_f32_e32 v8, v123, v123
	v_fmac_f32_e32 v9, v139, v139
	v_fmac_f32_e32 v10, v155, v155
	v_fmac_f32_e32 v11, v171, v171
	v_fmac_f32_e32 v8, v124, v124
	v_fmac_f32_e32 v9, v140, v140
	v_fmac_f32_e32 v10, v156, v156
	v_fmac_f32_e32 v11, v172, v172
	v_fmac_f32_e32 v8, v125, v125
	v_fmac_f32_e32 v9, v141, v141
	v_fmac_f32_e32 v10, v157, v157
	v_fmac_f32_e32 v11, v173, v173
	v_fmac_f32_e32 v8, v126, v126
	v_fmac_f32_e32 v9, v142, v142
	v_fmac_f32_e32 v10, v158, v158
	v_fmac_f32_e32 v11, v174, v174
	v_fmac_f32_e32 v8, v127, v127
	v_fmac_f32_e32 v9, v143, v143
	v_fmac_f32_e32 v10, v159, v159
	v_fmac_f32_e32 v11, v175, v175
	v_fmac_f32_e32 v8, v128, v128
	v_fmac_f32_e32 v9, v144, v144
	v_fmac_f32_e32 v10, v160, v160
	v_fmac_f32_e32 v11, v176, v176
	v_fmac_f32_e32 v8, v129, v129
	v_fmac_f32_e32 v9, v145, v145
	v_fmac_f32_e32 v10, v161, v161
	v_fmac_f32_e32 v11, v177, v177
	v_fmac_f32_e32 v8, v130, v130
	v_fmac_f32_e32 v9, v146, v146
	v_fmac_f32_e32 v10, v162, v162
	v_fmac_f32_e32 v11, v178, v178
	v_fmac_f32_e32 v8, v131, v131
	v_fmac_f32_e32 v9, v147, v147
	v_fmac_f32_e32 v10, v163, v163
	v_fmac_f32_e32 v11, v179, v179
	ds_bpermute_b32 v12, v16, v8
	ds_bpermute_b32 v13, v16, v9
	ds_bpermute_b32 v14, v16, v10
	ds_bpermute_b32 v15, v16, v11
	s_waitcnt lgkmcnt(0)
	v_add_f32_e32 v8, v8, v12
	v_add_f32_e32 v9, v9, v13
	v_add_f32_e32 v10, v10, v14
	v_add_f32_e32 v11, v11, v15
	ds_bpermute_b32 v12, v17, v8
	ds_bpermute_b32 v13, v17, v9
	ds_bpermute_b32 v14, v17, v10
	ds_bpermute_b32 v15, v17, v11
	s_waitcnt lgkmcnt(0)
	v_add_f32_e32 v8, v8, v12
	v_add_f32_e32 v9, v9, v13
	v_add_f32_e32 v10, v10, v14
	v_add_f32_e32 v11, v11, v15
	ds_bpermute_b32 v12, v18, v8
	ds_bpermute_b32 v13, v18, v9
	ds_bpermute_b32 v14, v18, v10
	ds_bpermute_b32 v15, v18, v11
	s_waitcnt lgkmcnt(0)
	v_add_f32_e32 v8, v8, v12
	v_add_f32_e32 v9, v9, v13
	v_add_f32_e32 v10, v10, v14
	v_add_f32_e32 v11, v11, v15
	ds_bpermute_b32 v12, v19, v8
	ds_bpermute_b32 v13, v19, v9
	ds_bpermute_b32 v14, v19, v10
	ds_bpermute_b32 v15, v19, v11
	s_waitcnt lgkmcnt(0)
	v_add_f32_e32 v8, v8, v12
	v_add_f32_e32 v9, v9, v13
	v_add_f32_e32 v10, v10, v14
	v_add_f32_e32 v11, v11, v15
	ds_bpermute_b32 v12, v20, v8
	ds_bpermute_b32 v13, v20, v9
	ds_bpermute_b32 v14, v20, v10
	ds_bpermute_b32 v15, v20, v11
	s_waitcnt lgkmcnt(0)
	v_add_f32_e32 v8, v8, v12
	v_add_f32_e32 v9, v9, v13
	v_add_f32_e32 v10, v10, v14
	v_add_f32_e32 v11, v11, v15
	ds_bpermute_b32 v12, v21, v8
	ds_bpermute_b32 v13, v21, v9
	ds_bpermute_b32 v14, v21, v10
	ds_bpermute_b32 v15, v21, v11
	s_waitcnt lgkmcnt(0)
	v_add_f32_e32 v8, v8, v12
	v_add_f32_e32 v9, v9, v13
	v_add_f32_e32 v10, v10, v14
	v_add_f32_e32 v11, v11, v15
	v_fmamk_f32 v8, v8, 0x3a800000, v220
	v_fmamk_f32 v9, v9, 0x3a800000, v220
	v_fmamk_f32 v10, v10, 0x3a800000, v220
	v_fmamk_f32 v11, v11, 0x3a800000, v220
	v_mul_f32_e32 v12, 0x4b800000, v8
	v_mul_f32_e32 v13, 0x4b800000, v9
	v_mul_f32_e32 v14, 0x4b800000, v10
	v_mul_f32_e32 v15, 0x4b800000, v11
	v_cmp_gt_f32_e32 vcc, s7, v8
	s_nop 1
	v_cndmask_b32_e32 v8, v8, v12, vcc
	v_rsq_f32_e32 v212, v8
	s_nop 0
	v_mul_f32_e32 v216, 0x45800000, v212
	v_cndmask_b32_e32 v212, v212, v216, vcc
	v_cmp_gt_f32_e32 vcc, s7, v9
	s_nop 1
	v_cndmask_b32_e32 v9, v9, v13, vcc
	v_rsq_f32_e32 v213, v9
	s_nop 0
	v_mul_f32_e32 v216, 0x45800000, v213
	v_cndmask_b32_e32 v213, v213, v216, vcc
	v_cmp_gt_f32_e32 vcc, s7, v10
	s_nop 1
	v_cndmask_b32_e32 v10, v10, v14, vcc
	v_rsq_f32_e32 v214, v10
	s_nop 0
	v_mul_f32_e32 v216, 0x45800000, v214
	v_cndmask_b32_e32 v214, v214, v216, vcc
	v_cmp_gt_f32_e32 vcc, s7, v11
	s_nop 1
	v_cndmask_b32_e32 v11, v11, v15, vcc
	v_rsq_f32_e32 v215, v11
	s_nop 0
	v_mul_f32_e32 v216, 0x45800000, v215
	v_cndmask_b32_e32 v215, v215, v216, vcc
	s_lshl_b32 s6, s16, 11
	s_add_u32 s26, s46, s6
	s_addc_u32 s27, s47, 0
	s_add_u32 s30, s26, 0x1000
	s_addc_u32 s31, s27, 0
	v_mul_f32_e32 v116, v116, v212
	v_mul_f32_e32 v117, v117, v212
	v_mul_f32_e32 v118, v118, v212
	v_mul_f32_e32 v119, v119, v212
	v_mul_f32_e32 v120, v120, v212
	v_mul_f32_e32 v121, v121, v212
	v_mul_f32_e32 v122, v122, v212
	v_mul_f32_e32 v123, v123, v212
	v_mul_f32_e32 v124, v124, v212
	v_mul_f32_e32 v125, v125, v212
	v_mul_f32_e32 v126, v126, v212
	v_mul_f32_e32 v127, v127, v212
	v_mul_f32_e32 v128, v128, v212
	v_mul_f32_e32 v129, v129, v212
	v_mul_f32_e32 v130, v130, v212
	v_mul_f32_e32 v131, v131, v212
	v_mul_f32_e32 v116, v100, v116
	v_mul_f32_e32 v117, v101, v117
	v_mul_f32_e32 v118, v102, v118
	v_mul_f32_e32 v119, v103, v119
	v_mul_f32_e32 v120, v104, v120
	v_mul_f32_e32 v121, v105, v121
	v_mul_f32_e32 v122, v106, v122
	v_mul_f32_e32 v123, v107, v123
	v_mul_f32_e32 v124, v108, v124
	v_mul_f32_e32 v125, v109, v125
	v_mul_f32_e32 v126, v110, v126
	v_mul_f32_e32 v127, v111, v127
	v_mul_f32_e32 v128, v112, v128
	v_mul_f32_e32 v129, v113, v129
	v_mul_f32_e32 v130, v114, v130
	v_mul_f32_e32 v131, v115, v131
	v_cvt_pk_bf16_f32 v180, v116, v117
	v_cvt_pk_bf16_f32 v181, v118, v119
	v_cvt_pk_bf16_f32 v182, v120, v121
	v_cvt_pk_bf16_f32 v183, v122, v123
	v_cvt_pk_bf16_f32 v184, v124, v125
	v_cvt_pk_bf16_f32 v185, v126, v127
	v_cvt_pk_bf16_f32 v186, v128, v129
	v_cvt_pk_bf16_f32 v187, v130, v131
	global_store_dwordx4 v23, v[180:183], s[26:27]
	global_store_dwordx4 v23, v[184:187], s[26:27] offset:1024
	v_mul_f32_e32 v132, v132, v213
	v_mul_f32_e32 v133, v133, v213
	v_mul_f32_e32 v134, v134, v213
	v_mul_f32_e32 v135, v135, v213
	v_mul_f32_e32 v136, v136, v213
	v_mul_f32_e32 v137, v137, v213
	v_mul_f32_e32 v138, v138, v213
	v_mul_f32_e32 v139, v139, v213
	v_mul_f32_e32 v140, v140, v213
	v_mul_f32_e32 v141, v141, v213
	v_mul_f32_e32 v142, v142, v213
	v_mul_f32_e32 v143, v143, v213
	v_mul_f32_e32 v144, v144, v213
	v_mul_f32_e32 v145, v145, v213
	v_mul_f32_e32 v146, v146, v213
	v_mul_f32_e32 v147, v147, v213
	v_mul_f32_e32 v132, v100, v132
	v_mul_f32_e32 v133, v101, v133
	v_mul_f32_e32 v134, v102, v134
	v_mul_f32_e32 v135, v103, v135
	v_mul_f32_e32 v136, v104, v136
	v_mul_f32_e32 v137, v105, v137
	v_mul_f32_e32 v138, v106, v138
	v_mul_f32_e32 v139, v107, v139
	v_mul_f32_e32 v140, v108, v140
	v_mul_f32_e32 v141, v109, v141
	v_mul_f32_e32 v142, v110, v142
	v_mul_f32_e32 v143, v111, v143
	v_mul_f32_e32 v144, v112, v144
	v_mul_f32_e32 v145, v113, v145
	v_mul_f32_e32 v146, v114, v146
	v_mul_f32_e32 v147, v115, v147
	v_cvt_pk_bf16_f32 v188, v132, v133
	v_cvt_pk_bf16_f32 v189, v134, v135
	v_cvt_pk_bf16_f32 v190, v136, v137
	v_cvt_pk_bf16_f32 v191, v138, v139
	v_cvt_pk_bf16_f32 v192, v140, v141
	v_cvt_pk_bf16_f32 v193, v142, v143
	v_cvt_pk_bf16_f32 v194, v144, v145
	v_cvt_pk_bf16_f32 v195, v146, v147
	global_store_dwordx4 v23, v[188:191], s[26:27] offset:2048
	global_store_dwordx4 v23, v[192:195], s[26:27] offset:3072
	v_mul_f32_e32 v148, v148, v214
	v_mul_f32_e32 v149, v149, v214
	v_mul_f32_e32 v150, v150, v214
	v_mul_f32_e32 v151, v151, v214
	v_mul_f32_e32 v152, v152, v214
	v_mul_f32_e32 v153, v153, v214
	v_mul_f32_e32 v154, v154, v214
	v_mul_f32_e32 v155, v155, v214
	v_mul_f32_e32 v156, v156, v214
	v_mul_f32_e32 v157, v157, v214
	v_mul_f32_e32 v158, v158, v214
	v_mul_f32_e32 v159, v159, v214
	v_mul_f32_e32 v160, v160, v214
	v_mul_f32_e32 v161, v161, v214
	v_mul_f32_e32 v162, v162, v214
	v_mul_f32_e32 v163, v163, v214
	v_mul_f32_e32 v148, v100, v148
	v_mul_f32_e32 v149, v101, v149
	v_mul_f32_e32 v150, v102, v150
	v_mul_f32_e32 v151, v103, v151
	v_mul_f32_e32 v152, v104, v152
	v_mul_f32_e32 v153, v105, v153
	v_mul_f32_e32 v154, v106, v154
	v_mul_f32_e32 v155, v107, v155
	v_mul_f32_e32 v156, v108, v156
	v_mul_f32_e32 v157, v109, v157
	v_mul_f32_e32 v158, v110, v158
	v_mul_f32_e32 v159, v111, v159
	v_mul_f32_e32 v160, v112, v160
	v_mul_f32_e32 v161, v113, v161
	v_mul_f32_e32 v162, v114, v162
	v_mul_f32_e32 v163, v115, v163
	v_cvt_pk_bf16_f32 v196, v148, v149
	v_cvt_pk_bf16_f32 v197, v150, v151
	v_cvt_pk_bf16_f32 v198, v152, v153
	v_cvt_pk_bf16_f32 v199, v154, v155
	v_cvt_pk_bf16_f32 v200, v156, v157
	v_cvt_pk_bf16_f32 v201, v158, v159
	v_cvt_pk_bf16_f32 v202, v160, v161
	v_cvt_pk_bf16_f32 v203, v162, v163
	global_store_dwordx4 v23, v[196:199], s[30:31]
	global_store_dwordx4 v23, v[200:203], s[30:31] offset:1024
	v_mul_f32_e32 v164, v164, v215
	v_mul_f32_e32 v165, v165, v215
	v_mul_f32_e32 v166, v166, v215
	v_mul_f32_e32 v167, v167, v215
	v_mul_f32_e32 v168, v168, v215
	v_mul_f32_e32 v169, v169, v215
	v_mul_f32_e32 v170, v170, v215
	v_mul_f32_e32 v171, v171, v215
	v_mul_f32_e32 v172, v172, v215
	v_mul_f32_e32 v173, v173, v215
	v_mul_f32_e32 v174, v174, v215
	v_mul_f32_e32 v175, v175, v215
	v_mul_f32_e32 v176, v176, v215
	v_mul_f32_e32 v177, v177, v215
	v_mul_f32_e32 v178, v178, v215
	v_mul_f32_e32 v179, v179, v215
	v_mul_f32_e32 v164, v100, v164
	v_mul_f32_e32 v165, v101, v165
	v_mul_f32_e32 v166, v102, v166
	v_mul_f32_e32 v167, v103, v167
	v_mul_f32_e32 v168, v104, v168
	v_mul_f32_e32 v169, v105, v169
	v_mul_f32_e32 v170, v106, v170
	v_mul_f32_e32 v171, v107, v171
	v_mul_f32_e32 v172, v108, v172
	v_mul_f32_e32 v173, v109, v173
	v_mul_f32_e32 v174, v110, v174
	v_mul_f32_e32 v175, v111, v175
	v_mul_f32_e32 v176, v112, v176
	v_mul_f32_e32 v177, v113, v177
	v_mul_f32_e32 v178, v114, v178
	v_mul_f32_e32 v179, v115, v179
	v_cvt_pk_bf16_f32 v204, v164, v165
	v_cvt_pk_bf16_f32 v205, v166, v167
	v_cvt_pk_bf16_f32 v206, v168, v169
	v_cvt_pk_bf16_f32 v207, v170, v171
	v_cvt_pk_bf16_f32 v208, v172, v173
	v_cvt_pk_bf16_f32 v209, v174, v175
	v_cvt_pk_bf16_f32 v210, v176, v177
	v_cvt_pk_bf16_f32 v211, v178, v179
	global_store_dwordx4 v23, v[204:207], s[30:31] offset:2048
	global_store_dwordx4 v23, v[208:211], s[30:31] offset:3072
	s_branch .Lrms_done
.Lrms_done:
.LBB0_362:
	s_or_b64 exec, exec, s[8:9]
	s_load_dword s4, s[0:1], 0x90
	s_waitcnt lgkmcnt(0)
	s_cmp_eq_u32 s4, 0x7fffffff
	s_cbranch_scc0 .LBB0_374
	v_lshrrev_b32_e32 v2, 20, v0
	v_lshrrev_b32_e32 v0, 10, v0
	v_or_b32_e32 v0, v0, v2
	s_movk_i32 s4, 0x3ff
	v_and_or_b32 v0, v0, s4, v238
	v_cmp_eq_u32_e32 vcc, 0, v0
	s_barrier
	s_and_saveexec_b64 s[4:5], vcc
	s_cbranch_execz .LBB0_373
	buffer_wbl2 sc1
	s_waitcnt vmcnt(0)
	s_load_dwordx2 s[6:7], s[28:29], 0x58
	v_mov_b32_e32 v3, 0
	s_mov_b64 s[8:9], exec
	v_mbcnt_lo_u32_b32 v2, s8, 0
	v_mbcnt_hi_u32_b32 v2, s9, v2
	s_waitcnt lgkmcnt(0)
	global_load_dword v0, v3, s[6:7] offset:40
	v_cmp_eq_u32_e32 vcc, 0, v2
	s_and_saveexec_b64 s[10:11], vcc
	s_cbranch_execz .LBB0_366
	s_bcnt1_i32_b64 s8, s[8:9]
	v_mov_b32_e32 v4, s8
	global_atomic_add v4, v3, v4, s[6:7] offset:32 sc0
